# page loop with 4 register batches (3 in flight), one log-f load per batch via quad DPP suffix sums, last iteration peeled (no out-of-range loads)
# baseline (speedup 1.0000x reference)
.LBB0_322:
	v_mov_b32_e32 v120, v158
	s_load_dwordx2 s[4:5], s[42:43], 0x40
	s_load_dwordx2 s[2:3], s[42:43], 0x100
	s_ashr_i32 s41, s40, 31
	s_ashr_i32 s1, s40, 6
	s_lshl_b64 s[6:7], s[40:41], 2
	s_waitcnt lgkmcnt(0)
	s_add_u32 s4, s4, s6
	s_addc_u32 s5, s5, s7
	global_load_dword v4, v1, s[4:5]
	s_load_dwordx4 s[4:7], s[42:43], 0x10
	s_load_dwordx2 s[8:9], s[42:43], 0x20
	s_mul_i32 s11, s74, 0xa00
	s_mul_i32 s10, s1, 0x5800
	v_ashrrev_i32_e32 v160, 4, v120
	v_lshlrev_b32_e32 v2, 6, v160
	v_ashrrev_i32_e32 v3, 31, v2
	v_lshlrev_b64 v[2:3], 1, v[2:3]
	v_and_b32_e32 v159, 15, v120
	v_lshlrev_b32_e32 v0, 3, v159
	v_ashrrev_i32_e32 v121, 31, v120
	s_mov_b32 s38, s14
	s_mov_b32 s39, s14
	v_lshlrev_b32_e32 v161, 4, v120
	s_mov_b32 s22, 0x1e400
	s_mov_b32 s28, 0x1d000
	s_mov_b32 s29, 0x1d400
	s_mov_b32 s35, 0x1d800
	s_mov_b32 s41, 0x1dc00
	v_lshlrev_b32_e32 v162, 2, v160
	v_mov_b32_e32 v118, 0
	s_mov_b32 s15, s14
	s_mov_b32 s19, s14
	v_mov_b32_e32 v151, 0xf149f2ca
	v_mov_b32_e32 v124, v118
	v_mov_b32_e32 v125, v118
	v_mov_b32_e32 v128, v118
	v_mov_b32_e32 v129, v118
	v_mov_b32_e32 v126, v118
	v_mov_b32_e32 v127, v118
	v_mov_b32_e32 v132, v118
	v_mov_b32_e32 v133, v118
	v_mov_b32_e32 v130, v118
	v_mov_b32_e32 v131, v118
	v_mov_b32_e32 v150, 0xf149f2ca
	v_mov_b32_e32 v144, 0xf149f2ca
	v_mov_b32_e32 v142, 0xf149f2ca
	s_waitcnt vmcnt(0)
	v_readfirstlane_b32 s0, v4
	s_add_i32 s16, s0, s11
	s_ashr_i32 s17, s16, 31
	s_lshl_b64 s[24:25], s[16:17], 17
	s_waitcnt lgkmcnt(0)
	s_add_u32 s12, s4, s24
	s_addc_u32 s0, s5, s25
	s_and_b32 s13, s0, 0xffff
	s_add_u32 s4, s6, s24
	s_addc_u32 s0, s7, s25
	s_lshl_b64 s[6:7], s[16:17], 11
	s_and_b32 s5, s0, 0xffff
	s_add_u32 s16, s8, s6
	s_addc_u32 s6, s9, s7
	s_lshl_b32 s8, s1, 2
	s_and_b32 s0, s40, 63
	s_add_i32 s7, s10, 0x5800000
	s_and_b32 s17, s6, 0xffff
	s_add_i32 s6, s8, 0x4000
	s_mul_hi_i32 s9, s6, 0x1600
	s_add_u32 s6, s2, s7
	s_addc_u32 s7, s3, s9
	s_add_i32 s9, s8, 0x4001
	s_add_i32 s11, s10, 0x5801600
	v_lshl_add_u64 v[4:5], s[6:7], 0, v[2:3]
	s_mul_hi_i32 s7, s9, 0x1600
	s_add_u32 s6, s2, s11
	s_addc_u32 s7, s3, s7
	s_add_i32 s9, s8, 0x4002
	s_add_i32 s10, s10, 0x5802c00
	v_lshl_add_u64 v[4:5], v[4:5], 0, v[0:1]
	s_mov_b32 s11, 0xb600000
	v_lshl_add_u64 v[6:7], s[6:7], 0, v[2:3]
	s_mul_hi_i32 s7, s9, 0x1600
	s_add_u32 s6, s2, s10
	v_add_co_u32_e32 v4, vcc, s11, v4
	s_addc_u32 s7, s3, s7
	s_addk_i32 s8, 0x4003
	v_addc_co_u32_e32 v5, vcc, 0, v5, vcc
	v_lshl_add_u64 v[6:7], v[6:7], 0, v[0:1]
	v_lshl_add_u64 v[8:9], s[6:7], 0, v[2:3]
	s_mul_hi_i32 s7, s8, 0x1600
	s_mulk_i32 s8, 0x1600
	v_add_co_u32_e32 v6, vcc, s11, v6
	s_add_u32 s6, s2, s8
	s_nop 0
	v_addc_co_u32_e32 v7, vcc, 0, v7, vcc
	v_lshl_add_u64 v[8:9], v[8:9], 0, v[0:1]
	s_addc_u32 s7, s3, s7
	s_add_i32 s8, s1, s20
	v_add_co_u32_e32 v8, vcc, s11, v8
	v_lshl_add_u64 v[2:3], s[6:7], 0, v[2:3]
	s_ashr_i32 s9, s8, 31
	v_addc_co_u32_e32 v9, vcc, 0, v9, vcc
	v_lshl_add_u64 v[2:3], v[2:3], 0, v[0:1]
	s_lshl_b64 s[6:7], s[8:9], 10
	v_add_co_u32_e32 v2, vcc, s11, v2
	s_add_u32 s2, s2, s6
	s_nop 0
	v_addc_co_u32_e32 v3, vcc, 0, v3, vcc
	s_addc_u32 s3, s3, s7
	global_load_dwordx2 v[106:107], v[4:5], off offset:2560
	global_load_dwordx2 v[104:105], v[6:7], off offset:2560
	global_load_dwordx2 v[102:103], v[8:9], off offset:2560
	global_load_dwordx2 v[122:123], v[2:3], off offset:2560
	v_lshl_add_u64 v[2:3], v[120:121], 4, s[2:3]
	s_mov_b32 s1, 0x3080000
	v_add_co_u32_e32 v2, vcc, s1, v2
	s_mov_b32 s36, s12
	s_nop 0
	v_addc_co_u32_e32 v3, vcc, 0, v3, vcc
	global_load_dwordx4 v[98:101], v[2:3], off
	s_mov_b32 s37, s13
	s_mov_b32 s3, 0x1f400
	s_mov_b32 s8, 0x1f800
	s_mov_b32 s2, 0x1f000
	s_mov_b32 s1, 0x1e000
	s_mov_b32 s9, 0x1fc00
	s_mov_b32 s24, 0x1e800
	s_mov_b32 s25, 0x1ec00
	s_mov_b32 s6, s14
	s_mov_b32 s7, s14
	s_mov_b32 s10, s18
	s_mov_b32 s11, s14
	v_and_b32_e32 v209, 3, v159
	v_lshl_add_u32 v162, v209, 4, v162
	s_mov_b32 s10, 0x1f000
	buffer_load_dwordx4 v[50:53], v161, s[36:39], s10 offen nt
	buffer_load_dwordx4 v[22:25], v161, s[4:7], s10 offen nt
	s_mov_b32 s10, 0x1f400
	buffer_load_dwordx4 v[58:61], v161, s[36:39], s10 offen nt
	buffer_load_dwordx4 v[18:21], v161, s[4:7], s10 offen nt
	s_mov_b32 s10, 0x1f800
	buffer_load_dwordx4 v[54:57], v161, s[36:39], s10 offen nt
	buffer_load_dwordx4 v[26:29], v161, s[4:7], s10 offen nt
	s_mov_b32 s10, 0x1fc00
	buffer_load_dwordx4 v[62:65], v161, s[36:39], s10 offen nt
	buffer_load_dwordx4 v[30:33], v161, s[4:7], s10 offen nt
	s_movk_i32 s10, 0x7c0
	buffer_load_dword v163, v162, s[16:19], s10 offen
	s_mov_b32 s10, 0x1e000
	buffer_load_dwordx4 v[34:37], v161, s[36:39], s10 offen nt
	buffer_load_dwordx4 v[2:5], v161, s[4:7], s10 offen nt
	s_mov_b32 s10, 0x1e400
	buffer_load_dwordx4 v[42:45], v161, s[36:39], s10 offen nt
	buffer_load_dwordx4 v[6:9], v161, s[4:7], s10 offen nt
	s_mov_b32 s10, 0x1e800
	buffer_load_dwordx4 v[38:41], v161, s[36:39], s10 offen nt
	buffer_load_dwordx4 v[10:13], v161, s[4:7], s10 offen nt
	s_mov_b32 s10, 0x1ec00
	buffer_load_dwordx4 v[46:49], v161, s[36:39], s10 offen nt
	buffer_load_dwordx4 v[14:17], v161, s[4:7], s10 offen nt
	s_movk_i32 s10, 0x780
	buffer_load_dword v164, v162, s[16:19], s10 offen
	s_mov_b32 s10, 0x1d000
	buffer_load_dwordx4 v[82:85], v161, s[36:39], s10 offen nt
	buffer_load_dwordx4 v[66:69], v161, s[4:7], s10 offen nt
	s_mov_b32 s10, 0x1d400
	buffer_load_dwordx4 v[86:89], v161, s[36:39], s10 offen nt
	buffer_load_dwordx4 v[70:73], v161, s[4:7], s10 offen nt
	s_mov_b32 s10, 0x1d800
	buffer_load_dwordx4 v[90:93], v161, s[36:39], s10 offen nt
	buffer_load_dwordx4 v[74:77], v161, s[4:7], s10 offen nt
	s_mov_b32 s10, 0x1dc00
	buffer_load_dwordx4 v[94:97], v161, s[36:39], s10 offen nt
	buffer_load_dwordx4 v[78:81], v161, s[4:7], s10 offen nt
	s_movk_i32 s10, 0x740
	buffer_load_dword v165, v162, s[16:19], s10 offen
	s_mov_b32 s10, 0x1c000
	buffer_load_dwordx4 v[210:213], v161, s[36:39], s10 offen nt
	buffer_load_dwordx4 v[250:253], v161, s[4:7], s10 offen nt
	s_mov_b32 s10, 0x1c400
	buffer_load_dwordx4 v[226:229], v161, s[36:39], s10 offen nt
	s_mov_b32 s10, 0x1c800
	buffer_load_dwordx4 v[230:233], v161, s[36:39], s10 offen nt
	buffer_load_dwordx4 v[174:177], v161, s[4:7], s10 offen nt
	s_mov_b32 s10, 0x1cc00
	buffer_load_dwordx4 v[234:237], v161, s[36:39], s10 offen nt
	buffer_load_dwordx4 v[168:171], v161, s[4:7], s10 offen nt
	s_movk_i32 s10, 0x700
	buffer_load_dword v166, v162, s[16:19], s10 offen
	v_cmp_lt_i32_e32 vcc, s0, v120
	v_lshlrev_b32_e32 v0, 2, v159
	s_waitcnt vmcnt(39)
	v_lshlrev_b32_e32 v114, 16, v106
	v_and_b32_e32 v115, 0xffff0000, v106
	v_lshlrev_b32_e32 v116, 16, v107
	v_and_b32_e32 v117, 0xffff0000, v107
	s_waitcnt vmcnt(38)
	v_lshlrev_b32_e32 v110, 16, v104
	v_and_b32_e32 v111, 0xffff0000, v104
	v_lshlrev_b32_e32 v112, 16, v105
	v_and_b32_e32 v113, 0xffff0000, v105
	s_waitcnt vmcnt(37)
	v_lshlrev_b32_e32 v106, 16, v102
	v_and_b32_e32 v107, 0xffff0000, v102
	v_lshlrev_b32_e32 v108, 16, v103
	s_waitcnt vmcnt(35)
	v_cndmask_b32_e32 v99, 0, v99, vcc
	v_cndmask_b32_e32 v98, 0, v98, vcc
	v_cndmask_b32_e32 v100, 0, v100, vcc
	v_add_f32_dpp v99, v99, v99 quad_perm:[1,0,3,2] row_mask:0xf bank_mask:0xf bound_ctrl:1
	v_cndmask_b32_e32 v101, 0, v101, vcc
	v_add_f32_dpp v98, v98, v98 quad_perm:[1,0,3,2] row_mask:0xf bank_mask:0xf bound_ctrl:1
	v_add_f32_dpp v99, v99, v99 quad_perm:[2,3,0,1] row_mask:0xf bank_mask:0xf bound_ctrl:1
	v_add_f32_dpp v100, v100, v100 quad_perm:[1,0,3,2] row_mask:0xf bank_mask:0xf bound_ctrl:1
	v_add_f32_dpp v101, v101, v101 quad_perm:[1,0,3,2] row_mask:0xf bank_mask:0xf bound_ctrl:1
	v_add_f32_dpp v98, v98, v98 quad_perm:[2,3,0,1] row_mask:0xf bank_mask:0xf bound_ctrl:1
	v_add_f32_dpp v99, v99, v99 row_half_mirror row_mask:0xf bank_mask:0xf bound_ctrl:1
	v_add_f32_dpp v100, v100, v100 quad_perm:[2,3,0,1] row_mask:0xf bank_mask:0xf bound_ctrl:1
	v_add_f32_dpp v101, v101, v101 quad_perm:[2,3,0,1] row_mask:0xf bank_mask:0xf bound_ctrl:1
	v_add_f32_dpp v98, v98, v98 row_half_mirror row_mask:0xf bank_mask:0xf bound_ctrl:1
	v_add_f32_dpp v99, v99, v99 row_mirror row_mask:0xf bank_mask:0xf bound_ctrl:1
	v_add_f32_dpp v100, v100, v100 row_half_mirror row_mask:0xf bank_mask:0xf bound_ctrl:1
	v_add_f32_dpp v101, v101, v101 row_half_mirror row_mask:0xf bank_mask:0xf bound_ctrl:1
	v_add_f32_dpp v98, v98, v98 row_mirror row_mask:0xf bank_mask:0xf bound_ctrl:1
	v_readlane_b32 s9, v99, 16
	v_readlane_b32 s22, v99, 48
	v_add_f32_dpp v100, v100, v100 row_mirror row_mask:0xf bank_mask:0xf bound_ctrl:1
	v_add_f32_dpp v119, v101, v101 row_mirror row_mask:0xf bank_mask:0xf bound_ctrl:1
	v_readlane_b32 s0, v98, 0
	v_readlane_b32 s10, v98, 16
	v_readlane_b32 s1, v98, 32
	v_readlane_b32 s11, v98, 48
	v_readlane_b32 s2, v99, 0
	v_readlane_b32 s3, v99, 32
	v_mov_b32_e32 v98, s9
	v_mov_b32_e32 v99, s22
	v_readlane_b32 s24, v100, 16
	v_readlane_b32 s25, v100, 48
	v_pk_add_f32 v[98:99], s[2:3], v[98:99]
	v_readlane_b32 s2, v119, 16
	v_readlane_b32 s3, v119, 48
	v_readlane_b32 s6, v100, 0
	v_readlane_b32 s7, v100, 32
	v_readlane_b32 s8, v119, 0
	v_mov_b32_e32 v100, s24
	v_mov_b32_e32 v101, s25
	v_add_f32_e32 v121, v98, v99
	v_readlane_b32 s9, v119, 32
	v_mov_b32_e32 v98, s2
	v_mov_b32_e32 v99, s3
	v_pk_add_f32 v[100:101], s[6:7], v[100:101]
	v_pk_add_f32 v[98:99], s[8:9], v[98:99]
	v_add_f32_e32 v100, v100, v101
	v_add_f32_e32 v98, v98, v99
	v_cmp_eq_u32_e32 vcc, 2, v160
	v_mov_b32_e32 v99, s11
	v_and_b32_e32 v109, 0xffff0000, v103
	v_cndmask_b32_e32 v98, v98, v100, vcc
	v_cmp_eq_u32_e32 vcc, 1, v160
	v_lshlrev_b32_e32 v102, 16, v122
	v_and_b32_e32 v103, 0xffff0000, v122
	v_cndmask_b32_e32 v100, v98, v121, vcc
	v_mov_b32_e32 v98, s10
	v_pk_add_f32 v[98:99], s[0:1], v[98:99]
	v_cmp_gt_u32_e32 vcc, 16, v120
	v_add_f32_e32 v98, v98, v99
	v_lshlrev_b32_e32 v104, 16, v123
	v_and_b32_e32 v105, 0xffff0000, v123
	v_cndmask_b32_e32 v146, v100, v98, vcc
	s_movk_i32 s2, 0x88
	s_movk_i32 s3, 0x680
	s_mov_b32 s8, 0x1a000
	v_mov_b32_e32 v119, v118
	v_mov_b32_e32 v120, v118
	v_mov_b32_e32 v121, v118
	v_mov_b32_e32 v122, v118
	v_mov_b32_e32 v123, v118
	v_mov_b32_e32 v98, v118
	v_mov_b32_e32 v99, v118
	v_mov_b32_e32 v100, v118
	v_mov_b32_e32 v101, v118
	s_mov_b32 s6, s14
	s_mov_b32 s7, s15
	s_mov_b32 s0, 0x1c400
	buffer_load_dwordx4 v[98:101], v161, s[4:7], s0 offen nt
	v_and_b32_e32 v155, 1, v159
	v_and_b32_e32 v156, 2, v159
	v_cmp_ne_u32_e64 s[28:29], 0, v155
	v_cmp_ne_u32_e64 s[24:25], 0, v156
	s_mov_b32 s8, 0x1f000
	s_movk_i32 s3, 0x7c0
	s_movk_i32 s2, 7
	v_mov_b32_e32 v118, 0
	v_mov_b32_e32 v119, 0
	v_mov_b32_e32 v120, 0
	v_mov_b32_e32 v121, 0
	v_mov_b32_e32 v122, 0
	v_mov_b32_e32 v123, 0
	v_mov_b32_e32 v124, 0
	v_mov_b32_e32 v125, 0
	v_mov_b32_e32 v126, 0
	v_mov_b32_e32 v127, 0
	v_mov_b32_e32 v128, 0
	v_mov_b32_e32 v129, 0
	v_mov_b32_e32 v130, 0
	v_mov_b32_e32 v131, 0
	v_mov_b32_e32 v132, 0
	v_mov_b32_e32 v133, 0
	v_mov_b32_e32 v134, 0xf149f2ca
	v_mov_b32_e32 v135, 0
.Lpg_loop:
	s_waitcnt vmcnt(27)
	v_pk_mul_f32 v[156:157], v[116:117], v[52:53]
	v_pk_mul_f32 v[178:179], v[116:117], v[60:61]
	v_pk_mul_f32 v[180:181], v[116:117], v[56:57]
	v_pk_mul_f32 v[238:239], v[116:117], v[64:65]
	v_pk_fma_f32 v[156:157], v[114:115], v[50:51], v[156:157]
	v_pk_fma_f32 v[178:179], v[114:115], v[58:59], v[178:179]
	v_pk_fma_f32 v[180:181], v[114:115], v[54:55], v[180:181]
	v_pk_fma_f32 v[238:239], v[114:115], v[62:63], v[238:239]
	v_add_f32_e32 v136, v156, v157
	v_add_f32_e32 v137, v178, v179
	v_add_f32_e32 v138, v180, v181
	v_add_f32_e32 v139, v238, v239
	v_pk_mul_f32 v[156:157], v[112:113], v[52:53]
	v_pk_mul_f32 v[178:179], v[112:113], v[60:61]
	v_pk_mul_f32 v[180:181], v[112:113], v[56:57]
	v_pk_mul_f32 v[238:239], v[112:113], v[64:65]
	v_pk_fma_f32 v[156:157], v[110:111], v[50:51], v[156:157]
	v_pk_fma_f32 v[178:179], v[110:111], v[58:59], v[178:179]
	v_pk_fma_f32 v[180:181], v[110:111], v[54:55], v[180:181]
	v_pk_fma_f32 v[238:239], v[110:111], v[62:63], v[238:239]
	v_add_f32_e32 v140, v156, v157
	v_add_f32_e32 v141, v178, v179
	v_add_f32_e32 v142, v180, v181
	v_add_f32_e32 v144, v238, v239
	v_pk_mul_f32 v[156:157], v[108:109], v[52:53]
	v_pk_mul_f32 v[178:179], v[108:109], v[60:61]
	v_pk_mul_f32 v[180:181], v[108:109], v[56:57]
	v_pk_mul_f32 v[238:239], v[108:109], v[64:65]
	v_pk_fma_f32 v[156:157], v[106:107], v[50:51], v[156:157]
	v_pk_fma_f32 v[178:179], v[106:107], v[58:59], v[178:179]
	v_pk_fma_f32 v[180:181], v[106:107], v[54:55], v[180:181]
	v_pk_fma_f32 v[238:239], v[106:107], v[62:63], v[238:239]
	v_add_f32_e32 v147, v156, v157
	v_add_f32_e32 v148, v178, v179
	v_add_f32_e32 v149, v180, v181
	v_add_f32_e32 v150, v238, v239
	v_pk_mul_f32 v[156:157], v[104:105], v[52:53]
	v_pk_mul_f32 v[178:179], v[104:105], v[60:61]
	v_pk_mul_f32 v[180:181], v[104:105], v[56:57]
	v_pk_mul_f32 v[238:239], v[104:105], v[64:65]
	v_pk_fma_f32 v[156:157], v[102:103], v[50:51], v[156:157]
	v_pk_fma_f32 v[178:179], v[102:103], v[58:59], v[178:179]
	v_pk_fma_f32 v[180:181], v[102:103], v[54:55], v[180:181]
	v_pk_fma_f32 v[238:239], v[102:103], v[62:63], v[238:239]
	v_add_f32_e32 v151, v156, v157
	v_add_f32_e32 v152, v178, v179
	v_add_f32_e32 v153, v180, v181
	v_add_f32_e32 v154, v238, v239
	v_mov_b32_dpp v143, v163 quad_perm:[1,2,3,3] row_mask:0xf bank_mask:0xf bound_ctrl:1
	v_add_f32_dpp v240, v163, v163 quad_perm:[1,0,3,2] row_mask:0xf bank_mask:0xf bound_ctrl:1
	v_cndmask_b32_e64 v209, v143, 0, s[28:29]
	v_add_f32_dpp v145, v163, v143 quad_perm:[2,3,3,3] row_mask:0xf bank_mask:0xf bound_ctrl:1
	v_add_f32_dpp v242, v240, v240 quad_perm:[2,3,0,1] row_mask:0xf bank_mask:0xf bound_ctrl:1
	v_add_f32_dpp v136, v136, v136 row_mirror row_mask:0xf bank_mask:0x3 bound_ctrl:1
	v_add_f32_dpp v137, v137, v137 row_mirror row_mask:0xf bank_mask:0x3 bound_ctrl:1
	v_add_f32_dpp v138, v138, v138 row_mirror row_mask:0xf bank_mask:0x3 bound_ctrl:1
	v_add_f32_dpp v139, v139, v139 row_mirror row_mask:0xf bank_mask:0x3 bound_ctrl:1
	v_add_f32_dpp v140, v140, v140 row_mirror row_mask:0xf bank_mask:0x3 bound_ctrl:1
	v_add_f32_dpp v141, v141, v141 row_mirror row_mask:0xf bank_mask:0x3 bound_ctrl:1
	v_add_f32_dpp v142, v142, v142 row_mirror row_mask:0xf bank_mask:0x3 bound_ctrl:1
	v_add_f32_dpp v144, v144, v144 row_mirror row_mask:0xf bank_mask:0x3 bound_ctrl:1
	v_add_f32_dpp v167, v163, v145 quad_perm:[3,3,3,3] row_mask:0xf bank_mask:0xf bound_ctrl:1
	v_add_f32_dpp v136, v147, v147 row_mirror row_mask:0xf bank_mask:0xc bound_ctrl:1
	v_add_f32_dpp v137, v148, v148 row_mirror row_mask:0xf bank_mask:0xc bound_ctrl:1
	v_add_f32_dpp v138, v149, v149 row_mirror row_mask:0xf bank_mask:0xc bound_ctrl:1
	v_add_f32_dpp v139, v150, v150 row_mirror row_mask:0xf bank_mask:0xc bound_ctrl:1
	v_add_f32_dpp v140, v151, v151 row_mirror row_mask:0xf bank_mask:0xc bound_ctrl:1
	v_add_f32_dpp v141, v152, v152 row_mirror row_mask:0xf bank_mask:0xc bound_ctrl:1
	v_add_f32_dpp v142, v153, v153 row_mirror row_mask:0xf bank_mask:0xc bound_ctrl:1
	v_add_f32_dpp v144, v154, v154 row_mirror row_mask:0xf bank_mask:0xc bound_ctrl:1
	v_add_f32_dpp v136, v136, v136 row_half_mirror row_mask:0xf bank_mask:0x5 bound_ctrl:1
	v_add_f32_dpp v137, v137, v137 row_half_mirror row_mask:0xf bank_mask:0x5 bound_ctrl:1
	v_add_f32_dpp v138, v138, v138 row_half_mirror row_mask:0xf bank_mask:0x5 bound_ctrl:1
	v_add_f32_dpp v139, v139, v139 row_half_mirror row_mask:0xf bank_mask:0x5 bound_ctrl:1
	v_add_f32_dpp v136, v140, v140 row_half_mirror row_mask:0xf bank_mask:0xa bound_ctrl:1
	v_add_f32_dpp v137, v141, v141 row_half_mirror row_mask:0xf bank_mask:0xa bound_ctrl:1
	v_add_f32_dpp v138, v142, v142 row_half_mirror row_mask:0xf bank_mask:0xa bound_ctrl:1
	v_add_f32_dpp v139, v144, v144 row_half_mirror row_mask:0xf bank_mask:0xa bound_ctrl:1
	v_add_f32_dpp v136, v136, v136 quad_perm:[2,3,0,1] row_mask:0xf bank_mask:0xf bound_ctrl:1
	v_add_f32_dpp v138, v138, v138 quad_perm:[2,3,0,1] row_mask:0xf bank_mask:0xf bound_ctrl:1
	v_add_f32_dpp v137, v137, v137 quad_perm:[2,3,0,1] row_mask:0xf bank_mask:0xf bound_ctrl:1
	v_add_f32_dpp v139, v139, v139 quad_perm:[2,3,0,1] row_mask:0xf bank_mask:0xf bound_ctrl:1
	v_cndmask_b32_e64 v167, v167, v145, s[28:29]
	v_cndmask_b32_e64 v172, v167, v209, s[24:25]
	v_cndmask_b32_e64 v136, v136, v138, s[24:25]
	v_cndmask_b32_e64 v137, v137, v139, s[24:25]
	v_add_f32_e32 v172, v146, v172
	v_add_f32_e32 v146, v146, v242
	v_add_f32_dpp v136, v136, v136 quad_perm:[1,0,3,2] row_mask:0xf bank_mask:0xf bound_ctrl:1
	v_add_f32_dpp v137, v137, v137 quad_perm:[1,0,3,2] row_mask:0xf bank_mask:0xf bound_ctrl:1
	v_cndmask_b32_e64 v136, v136, v137, s[28:29]
	v_fmac_f32_e32 v136, 0x3fb8aa3b, v172
	s_nop 1
	v_max_f32_dpp v179, v136, v136 quad_perm:[1,0,3,2] row_mask:0xf bank_mask:0xf bound_ctrl:1
	s_nop 1
	v_max_f32_dpp v180, v179, v179 quad_perm:[2,3,0,1] row_mask:0xf bank_mask:0xf bound_ctrl:1
	v_max_f32_e32 v180, v134, v180
	v_sub_f32_e32 v155, v134, v180
	v_sub_f32_e32 v156, v136, v180
	v_mov_b32_e32 v134, v180
	v_exp_f32_e32 v155, v155
	v_exp_f32_e32 v156, v156
	s_nop 0
	v_mov_b32_dpp v137, v155 row_newbcast:0 row_mask:0xf bank_mask:0xf
	v_mov_b32_dpp v142, v155 row_newbcast:4 row_mask:0xf bank_mask:0xf
	v_mov_b32_dpp v150, v155 row_newbcast:8 row_mask:0xf bank_mask:0xf
	v_mov_b32_dpp v178, v155 row_newbcast:12 row_mask:0xf bank_mask:0xf
	v_add_f32_dpp v157, v156, v156 quad_perm:[1,0,3,2] row_mask:0xf bank_mask:0xf bound_ctrl:1
	v_mov_b32_dpp v138, v156 row_newbcast:0 row_mask:0xf bank_mask:0xf
	v_mov_b32_dpp v139, v156 row_newbcast:1 row_mask:0xf bank_mask:0xf
	v_mov_b32_dpp v140, v156 row_newbcast:2 row_mask:0xf bank_mask:0xf
	v_mov_b32_dpp v141, v156 row_newbcast:3 row_mask:0xf bank_mask:0xf
	v_add_f32_dpp v173, v157, v157 quad_perm:[2,3,0,1] row_mask:0xf bank_mask:0xf bound_ctrl:1
	v_mov_b32_dpp v144, v156 row_newbcast:4 row_mask:0xf bank_mask:0xf
	v_mov_b32_dpp v147, v156 row_newbcast:5 row_mask:0xf bank_mask:0xf
	v_mov_b32_dpp v148, v156 row_newbcast:6 row_mask:0xf bank_mask:0xf
	v_mov_b32_dpp v149, v156 row_newbcast:7 row_mask:0xf bank_mask:0xf
	v_fma_f32 v135, v135, v155, v173
	v_mov_b32_dpp v151, v156 row_newbcast:8 row_mask:0xf bank_mask:0xf
	v_mov_b32_dpp v152, v156 row_newbcast:9 row_mask:0xf bank_mask:0xf
	v_mov_b32_dpp v153, v156 row_newbcast:10 row_mask:0xf bank_mask:0xf
	v_mov_b32_dpp v154, v156 row_newbcast:11 row_mask:0xf bank_mask:0xf
	v_mov_b32_dpp v179, v156 row_newbcast:12 row_mask:0xf bank_mask:0xf
	v_mov_b32_dpp v180, v156 row_newbcast:13 row_mask:0xf bank_mask:0xf
	v_mov_b32_dpp v181, v156 row_newbcast:14 row_mask:0xf bank_mask:0xf
	v_mov_b32_dpp v0, v156 row_newbcast:15 row_mask:0xf bank_mask:0xf
	v_pk_mul_f32 v[118:119], v[118:119], v[136:137] op_sel:[0,1] op_sel_hi:[1,1]
	v_pk_mul_f32 v[120:121], v[120:121], v[136:137] op_sel:[0,1] op_sel_hi:[1,1]
	v_pk_mul_f32 v[122:123], v[122:123], v[142:143] op_sel:[0,0] op_sel_hi:[1,0]
	v_pk_mul_f32 v[124:125], v[124:125], v[142:143] op_sel:[0,0] op_sel_hi:[1,0]
	v_pk_mul_f32 v[126:127], v[126:127], v[150:151] op_sel:[0,0] op_sel_hi:[1,0]
	v_pk_mul_f32 v[128:129], v[128:129], v[150:151] op_sel:[0,0] op_sel_hi:[1,0]
	v_pk_mul_f32 v[130:131], v[130:131], v[178:179] op_sel:[0,0] op_sel_hi:[1,0]
	v_pk_mul_f32 v[132:133], v[132:133], v[178:179] op_sel:[0,0] op_sel_hi:[1,0]
	v_pk_fma_f32 v[118:119], v[138:139], v[22:23], v[118:119] op_sel:[0,0,0] op_sel_hi:[0,1,1]
	v_pk_fma_f32 v[120:121], v[138:139], v[24:25], v[120:121] op_sel:[0,0,0] op_sel_hi:[0,1,1]
	v_pk_fma_f32 v[122:123], v[144:145], v[22:23], v[122:123] op_sel:[0,0,0] op_sel_hi:[0,1,1]
	v_pk_fma_f32 v[124:125], v[144:145], v[24:25], v[124:125] op_sel:[0,0,0] op_sel_hi:[0,1,1]
	v_pk_fma_f32 v[126:127], v[150:151], v[22:23], v[126:127] op_sel:[1,0,0] op_sel_hi:[1,1,1]
	v_pk_fma_f32 v[128:129], v[150:151], v[24:25], v[128:129] op_sel:[1,0,0] op_sel_hi:[1,1,1]
	v_pk_fma_f32 v[130:131], v[178:179], v[22:23], v[130:131] op_sel:[1,0,0] op_sel_hi:[1,1,1]
	v_pk_fma_f32 v[132:133], v[178:179], v[24:25], v[132:133] op_sel:[1,0,0] op_sel_hi:[1,1,1]
	v_pk_fma_f32 v[118:119], v[138:139], v[18:19], v[118:119] op_sel:[1,0,0] op_sel_hi:[1,1,1]
	v_pk_fma_f32 v[120:121], v[138:139], v[20:21], v[120:121] op_sel:[1,0,0] op_sel_hi:[1,1,1]
	v_pk_fma_f32 v[122:123], v[146:147], v[18:19], v[122:123] op_sel:[1,0,0] op_sel_hi:[1,1,1]
	v_pk_fma_f32 v[124:125], v[146:147], v[20:21], v[124:125] op_sel:[1,0,0] op_sel_hi:[1,1,1]
	v_pk_fma_f32 v[126:127], v[152:153], v[18:19], v[126:127] op_sel:[0,0,0] op_sel_hi:[0,1,1]
	v_pk_fma_f32 v[128:129], v[152:153], v[20:21], v[128:129] op_sel:[0,0,0] op_sel_hi:[0,1,1]
	v_pk_fma_f32 v[130:131], v[180:181], v[18:19], v[130:131] op_sel:[0,0,0] op_sel_hi:[0,1,1]
	v_pk_fma_f32 v[132:133], v[180:181], v[20:21], v[132:133] op_sel:[0,0,0] op_sel_hi:[0,1,1]
	v_pk_fma_f32 v[118:119], v[140:141], v[26:27], v[118:119] op_sel:[0,0,0] op_sel_hi:[0,1,1]
	v_pk_fma_f32 v[120:121], v[140:141], v[28:29], v[120:121] op_sel:[0,0,0] op_sel_hi:[0,1,1]
	v_pk_fma_f32 v[122:123], v[148:149], v[26:27], v[122:123] op_sel:[0,0,0] op_sel_hi:[0,1,1]
	v_pk_fma_f32 v[124:125], v[148:149], v[28:29], v[124:125] op_sel:[0,0,0] op_sel_hi:[0,1,1]
	v_pk_fma_f32 v[126:127], v[152:153], v[26:27], v[126:127] op_sel:[1,0,0] op_sel_hi:[1,1,1]
	v_pk_fma_f32 v[128:129], v[152:153], v[28:29], v[128:129] op_sel:[1,0,0] op_sel_hi:[1,1,1]
	v_pk_fma_f32 v[130:131], v[180:181], v[26:27], v[130:131] op_sel:[1,0,0] op_sel_hi:[1,1,1]
	v_pk_fma_f32 v[132:133], v[180:181], v[28:29], v[132:133] op_sel:[1,0,0] op_sel_hi:[1,1,1]
	v_pk_fma_f32 v[118:119], v[140:141], v[30:31], v[118:119] op_sel:[1,0,0] op_sel_hi:[1,1,1]
	v_pk_fma_f32 v[120:121], v[140:141], v[32:33], v[120:121] op_sel:[1,0,0] op_sel_hi:[1,1,1]
	v_pk_fma_f32 v[122:123], v[148:149], v[30:31], v[122:123] op_sel:[1,0,0] op_sel_hi:[1,1,1]
	v_pk_fma_f32 v[124:125], v[148:149], v[32:33], v[124:125] op_sel:[1,0,0] op_sel_hi:[1,1,1]
	v_pk_fma_f32 v[126:127], v[154:155], v[30:31], v[126:127] op_sel:[0,0,0] op_sel_hi:[0,1,1]
	v_pk_fma_f32 v[128:129], v[154:155], v[32:33], v[128:129] op_sel:[0,0,0] op_sel_hi:[0,1,1]
	v_pk_fma_f32 v[130:131], v[0:1], v[30:31], v[130:131] op_sel:[0,0,0] op_sel_hi:[0,1,1]
	v_pk_fma_f32 v[132:133], v[0:1], v[32:33], v[132:133] op_sel:[0,0,0] op_sel_hi:[0,1,1]
	s_sub_i32 s0, s8, 0x4000
	buffer_load_dwordx4 v[50:53], v161, s[12:15], s0 offen nt
	buffer_load_dwordx4 v[22:25], v161, s[4:7], s0 offen nt
	s_sub_i32 s0, s8, 0x3c00
	buffer_load_dwordx4 v[58:61], v161, s[12:15], s0 offen nt
	buffer_load_dwordx4 v[18:21], v161, s[4:7], s0 offen nt
	s_sub_i32 s0, s8, 0x3800
	buffer_load_dwordx4 v[54:57], v161, s[12:15], s0 offen nt
	buffer_load_dwordx4 v[26:29], v161, s[4:7], s0 offen nt
	s_sub_i32 s0, s8, 0x3400
	buffer_load_dwordx4 v[62:65], v161, s[12:15], s0 offen nt
	buffer_load_dwordx4 v[30:33], v161, s[4:7], s0 offen nt
	s_sub_i32 s0, s3, 0x100
	buffer_load_dword v163, v162, s[16:19], s0 offen
	s_waitcnt vmcnt(27)
	v_pk_mul_f32 v[156:157], v[116:117], v[36:37]
	v_pk_mul_f32 v[178:179], v[116:117], v[44:45]
	v_pk_mul_f32 v[180:181], v[116:117], v[40:41]
	v_pk_mul_f32 v[238:239], v[116:117], v[48:49]
	v_pk_fma_f32 v[156:157], v[114:115], v[34:35], v[156:157]
	v_pk_fma_f32 v[178:179], v[114:115], v[42:43], v[178:179]
	v_pk_fma_f32 v[180:181], v[114:115], v[38:39], v[180:181]
	v_pk_fma_f32 v[238:239], v[114:115], v[46:47], v[238:239]
	v_add_f32_e32 v136, v156, v157
	v_add_f32_e32 v137, v178, v179
	v_add_f32_e32 v138, v180, v181
	v_add_f32_e32 v139, v238, v239
	v_pk_mul_f32 v[156:157], v[112:113], v[36:37]
	v_pk_mul_f32 v[178:179], v[112:113], v[44:45]
	v_pk_mul_f32 v[180:181], v[112:113], v[40:41]
	v_pk_mul_f32 v[238:239], v[112:113], v[48:49]
	v_pk_fma_f32 v[156:157], v[110:111], v[34:35], v[156:157]
	v_pk_fma_f32 v[178:179], v[110:111], v[42:43], v[178:179]
	v_pk_fma_f32 v[180:181], v[110:111], v[38:39], v[180:181]
	v_pk_fma_f32 v[238:239], v[110:111], v[46:47], v[238:239]
	v_add_f32_e32 v140, v156, v157
	v_add_f32_e32 v141, v178, v179
	v_add_f32_e32 v142, v180, v181
	v_add_f32_e32 v144, v238, v239
	v_pk_mul_f32 v[156:157], v[108:109], v[36:37]
	v_pk_mul_f32 v[178:179], v[108:109], v[44:45]
	v_pk_mul_f32 v[180:181], v[108:109], v[40:41]
	v_pk_mul_f32 v[238:239], v[108:109], v[48:49]
	v_pk_fma_f32 v[156:157], v[106:107], v[34:35], v[156:157]
	v_pk_fma_f32 v[178:179], v[106:107], v[42:43], v[178:179]
	v_pk_fma_f32 v[180:181], v[106:107], v[38:39], v[180:181]
	v_pk_fma_f32 v[238:239], v[106:107], v[46:47], v[238:239]
	v_add_f32_e32 v147, v156, v157
	v_add_f32_e32 v148, v178, v179
	v_add_f32_e32 v149, v180, v181
	v_add_f32_e32 v150, v238, v239
	v_pk_mul_f32 v[156:157], v[104:105], v[36:37]
	v_pk_mul_f32 v[178:179], v[104:105], v[44:45]
	v_pk_mul_f32 v[180:181], v[104:105], v[40:41]
	v_pk_mul_f32 v[238:239], v[104:105], v[48:49]
	v_pk_fma_f32 v[156:157], v[102:103], v[34:35], v[156:157]
	v_pk_fma_f32 v[178:179], v[102:103], v[42:43], v[178:179]
	v_pk_fma_f32 v[180:181], v[102:103], v[38:39], v[180:181]
	v_pk_fma_f32 v[238:239], v[102:103], v[46:47], v[238:239]
	v_add_f32_e32 v151, v156, v157
	v_add_f32_e32 v152, v178, v179
	v_add_f32_e32 v153, v180, v181
	v_add_f32_e32 v154, v238, v239
	v_mov_b32_dpp v143, v164 quad_perm:[1,2,3,3] row_mask:0xf bank_mask:0xf bound_ctrl:1
	v_add_f32_dpp v240, v164, v164 quad_perm:[1,0,3,2] row_mask:0xf bank_mask:0xf bound_ctrl:1
	v_cndmask_b32_e64 v209, v143, 0, s[28:29]
	v_add_f32_dpp v145, v164, v143 quad_perm:[2,3,3,3] row_mask:0xf bank_mask:0xf bound_ctrl:1
	v_add_f32_dpp v242, v240, v240 quad_perm:[2,3,0,1] row_mask:0xf bank_mask:0xf bound_ctrl:1
	v_add_f32_dpp v136, v136, v136 row_mirror row_mask:0xf bank_mask:0x3 bound_ctrl:1
	v_add_f32_dpp v137, v137, v137 row_mirror row_mask:0xf bank_mask:0x3 bound_ctrl:1
	v_add_f32_dpp v138, v138, v138 row_mirror row_mask:0xf bank_mask:0x3 bound_ctrl:1
	v_add_f32_dpp v139, v139, v139 row_mirror row_mask:0xf bank_mask:0x3 bound_ctrl:1
	v_add_f32_dpp v140, v140, v140 row_mirror row_mask:0xf bank_mask:0x3 bound_ctrl:1
	v_add_f32_dpp v141, v141, v141 row_mirror row_mask:0xf bank_mask:0x3 bound_ctrl:1
	v_add_f32_dpp v142, v142, v142 row_mirror row_mask:0xf bank_mask:0x3 bound_ctrl:1
	v_add_f32_dpp v144, v144, v144 row_mirror row_mask:0xf bank_mask:0x3 bound_ctrl:1
	v_add_f32_dpp v167, v164, v145 quad_perm:[3,3,3,3] row_mask:0xf bank_mask:0xf bound_ctrl:1
	v_add_f32_dpp v136, v147, v147 row_mirror row_mask:0xf bank_mask:0xc bound_ctrl:1
	v_add_f32_dpp v137, v148, v148 row_mirror row_mask:0xf bank_mask:0xc bound_ctrl:1
	v_add_f32_dpp v138, v149, v149 row_mirror row_mask:0xf bank_mask:0xc bound_ctrl:1
	v_add_f32_dpp v139, v150, v150 row_mirror row_mask:0xf bank_mask:0xc bound_ctrl:1
	v_add_f32_dpp v140, v151, v151 row_mirror row_mask:0xf bank_mask:0xc bound_ctrl:1
	v_add_f32_dpp v141, v152, v152 row_mirror row_mask:0xf bank_mask:0xc bound_ctrl:1
	v_add_f32_dpp v142, v153, v153 row_mirror row_mask:0xf bank_mask:0xc bound_ctrl:1
	v_add_f32_dpp v144, v154, v154 row_mirror row_mask:0xf bank_mask:0xc bound_ctrl:1
	v_add_f32_dpp v136, v136, v136 row_half_mirror row_mask:0xf bank_mask:0x5 bound_ctrl:1
	v_add_f32_dpp v137, v137, v137 row_half_mirror row_mask:0xf bank_mask:0x5 bound_ctrl:1
	v_add_f32_dpp v138, v138, v138 row_half_mirror row_mask:0xf bank_mask:0x5 bound_ctrl:1
	v_add_f32_dpp v139, v139, v139 row_half_mirror row_mask:0xf bank_mask:0x5 bound_ctrl:1
	v_add_f32_dpp v136, v140, v140 row_half_mirror row_mask:0xf bank_mask:0xa bound_ctrl:1
	v_add_f32_dpp v137, v141, v141 row_half_mirror row_mask:0xf bank_mask:0xa bound_ctrl:1
	v_add_f32_dpp v138, v142, v142 row_half_mirror row_mask:0xf bank_mask:0xa bound_ctrl:1
	v_add_f32_dpp v139, v144, v144 row_half_mirror row_mask:0xf bank_mask:0xa bound_ctrl:1
	v_add_f32_dpp v136, v136, v136 quad_perm:[2,3,0,1] row_mask:0xf bank_mask:0xf bound_ctrl:1
	v_add_f32_dpp v138, v138, v138 quad_perm:[2,3,0,1] row_mask:0xf bank_mask:0xf bound_ctrl:1
	v_add_f32_dpp v137, v137, v137 quad_perm:[2,3,0,1] row_mask:0xf bank_mask:0xf bound_ctrl:1
	v_add_f32_dpp v139, v139, v139 quad_perm:[2,3,0,1] row_mask:0xf bank_mask:0xf bound_ctrl:1
	v_cndmask_b32_e64 v167, v167, v145, s[28:29]
	v_cndmask_b32_e64 v172, v167, v209, s[24:25]
	v_cndmask_b32_e64 v136, v136, v138, s[24:25]
	v_cndmask_b32_e64 v137, v137, v139, s[24:25]
	v_add_f32_e32 v172, v146, v172
	v_add_f32_e32 v146, v146, v242
	v_add_f32_dpp v136, v136, v136 quad_perm:[1,0,3,2] row_mask:0xf bank_mask:0xf bound_ctrl:1
	v_add_f32_dpp v137, v137, v137 quad_perm:[1,0,3,2] row_mask:0xf bank_mask:0xf bound_ctrl:1
	v_cndmask_b32_e64 v136, v136, v137, s[28:29]
	v_fmac_f32_e32 v136, 0x3fb8aa3b, v172
	s_nop 1
	v_max_f32_dpp v179, v136, v136 quad_perm:[1,0,3,2] row_mask:0xf bank_mask:0xf bound_ctrl:1
	s_nop 1
	v_max_f32_dpp v180, v179, v179 quad_perm:[2,3,0,1] row_mask:0xf bank_mask:0xf bound_ctrl:1
	v_max_f32_e32 v180, v134, v180
	v_sub_f32_e32 v155, v134, v180
	v_sub_f32_e32 v156, v136, v180
	v_mov_b32_e32 v134, v180
	v_exp_f32_e32 v155, v155
	v_exp_f32_e32 v156, v156
	s_nop 0
	v_mov_b32_dpp v137, v155 row_newbcast:0 row_mask:0xf bank_mask:0xf
	v_mov_b32_dpp v142, v155 row_newbcast:4 row_mask:0xf bank_mask:0xf
	v_mov_b32_dpp v150, v155 row_newbcast:8 row_mask:0xf bank_mask:0xf
	v_mov_b32_dpp v178, v155 row_newbcast:12 row_mask:0xf bank_mask:0xf
	v_add_f32_dpp v157, v156, v156 quad_perm:[1,0,3,2] row_mask:0xf bank_mask:0xf bound_ctrl:1
	v_mov_b32_dpp v138, v156 row_newbcast:0 row_mask:0xf bank_mask:0xf
	v_mov_b32_dpp v139, v156 row_newbcast:1 row_mask:0xf bank_mask:0xf
	v_mov_b32_dpp v140, v156 row_newbcast:2 row_mask:0xf bank_mask:0xf
	v_mov_b32_dpp v141, v156 row_newbcast:3 row_mask:0xf bank_mask:0xf
	v_add_f32_dpp v173, v157, v157 quad_perm:[2,3,0,1] row_mask:0xf bank_mask:0xf bound_ctrl:1
	v_mov_b32_dpp v144, v156 row_newbcast:4 row_mask:0xf bank_mask:0xf
	v_mov_b32_dpp v147, v156 row_newbcast:5 row_mask:0xf bank_mask:0xf
	v_mov_b32_dpp v148, v156 row_newbcast:6 row_mask:0xf bank_mask:0xf
	v_mov_b32_dpp v149, v156 row_newbcast:7 row_mask:0xf bank_mask:0xf
	v_fma_f32 v135, v135, v155, v173
	v_mov_b32_dpp v151, v156 row_newbcast:8 row_mask:0xf bank_mask:0xf
	v_mov_b32_dpp v152, v156 row_newbcast:9 row_mask:0xf bank_mask:0xf
	v_mov_b32_dpp v153, v156 row_newbcast:10 row_mask:0xf bank_mask:0xf
	v_mov_b32_dpp v154, v156 row_newbcast:11 row_mask:0xf bank_mask:0xf
	v_mov_b32_dpp v179, v156 row_newbcast:12 row_mask:0xf bank_mask:0xf
	v_mov_b32_dpp v180, v156 row_newbcast:13 row_mask:0xf bank_mask:0xf
	v_mov_b32_dpp v181, v156 row_newbcast:14 row_mask:0xf bank_mask:0xf
	v_mov_b32_dpp v0, v156 row_newbcast:15 row_mask:0xf bank_mask:0xf
	v_pk_mul_f32 v[118:119], v[118:119], v[136:137] op_sel:[0,1] op_sel_hi:[1,1]
	v_pk_mul_f32 v[120:121], v[120:121], v[136:137] op_sel:[0,1] op_sel_hi:[1,1]
	v_pk_mul_f32 v[122:123], v[122:123], v[142:143] op_sel:[0,0] op_sel_hi:[1,0]
	v_pk_mul_f32 v[124:125], v[124:125], v[142:143] op_sel:[0,0] op_sel_hi:[1,0]
	v_pk_mul_f32 v[126:127], v[126:127], v[150:151] op_sel:[0,0] op_sel_hi:[1,0]
	v_pk_mul_f32 v[128:129], v[128:129], v[150:151] op_sel:[0,0] op_sel_hi:[1,0]
	v_pk_mul_f32 v[130:131], v[130:131], v[178:179] op_sel:[0,0] op_sel_hi:[1,0]
	v_pk_mul_f32 v[132:133], v[132:133], v[178:179] op_sel:[0,0] op_sel_hi:[1,0]
	v_pk_fma_f32 v[118:119], v[138:139], v[2:3], v[118:119] op_sel:[0,0,0] op_sel_hi:[0,1,1]
	v_pk_fma_f32 v[120:121], v[138:139], v[4:5], v[120:121] op_sel:[0,0,0] op_sel_hi:[0,1,1]
	v_pk_fma_f32 v[122:123], v[144:145], v[2:3], v[122:123] op_sel:[0,0,0] op_sel_hi:[0,1,1]
	v_pk_fma_f32 v[124:125], v[144:145], v[4:5], v[124:125] op_sel:[0,0,0] op_sel_hi:[0,1,1]
	v_pk_fma_f32 v[126:127], v[150:151], v[2:3], v[126:127] op_sel:[1,0,0] op_sel_hi:[1,1,1]
	v_pk_fma_f32 v[128:129], v[150:151], v[4:5], v[128:129] op_sel:[1,0,0] op_sel_hi:[1,1,1]
	v_pk_fma_f32 v[130:131], v[178:179], v[2:3], v[130:131] op_sel:[1,0,0] op_sel_hi:[1,1,1]
	v_pk_fma_f32 v[132:133], v[178:179], v[4:5], v[132:133] op_sel:[1,0,0] op_sel_hi:[1,1,1]
	v_pk_fma_f32 v[118:119], v[138:139], v[6:7], v[118:119] op_sel:[1,0,0] op_sel_hi:[1,1,1]
	v_pk_fma_f32 v[120:121], v[138:139], v[8:9], v[120:121] op_sel:[1,0,0] op_sel_hi:[1,1,1]
	v_pk_fma_f32 v[122:123], v[146:147], v[6:7], v[122:123] op_sel:[1,0,0] op_sel_hi:[1,1,1]
	v_pk_fma_f32 v[124:125], v[146:147], v[8:9], v[124:125] op_sel:[1,0,0] op_sel_hi:[1,1,1]
	v_pk_fma_f32 v[126:127], v[152:153], v[6:7], v[126:127] op_sel:[0,0,0] op_sel_hi:[0,1,1]
	v_pk_fma_f32 v[128:129], v[152:153], v[8:9], v[128:129] op_sel:[0,0,0] op_sel_hi:[0,1,1]
	v_pk_fma_f32 v[130:131], v[180:181], v[6:7], v[130:131] op_sel:[0,0,0] op_sel_hi:[0,1,1]
	v_pk_fma_f32 v[132:133], v[180:181], v[8:9], v[132:133] op_sel:[0,0,0] op_sel_hi:[0,1,1]
	v_pk_fma_f32 v[118:119], v[140:141], v[10:11], v[118:119] op_sel:[0,0,0] op_sel_hi:[0,1,1]
	v_pk_fma_f32 v[120:121], v[140:141], v[12:13], v[120:121] op_sel:[0,0,0] op_sel_hi:[0,1,1]
	v_pk_fma_f32 v[122:123], v[148:149], v[10:11], v[122:123] op_sel:[0,0,0] op_sel_hi:[0,1,1]
	v_pk_fma_f32 v[124:125], v[148:149], v[12:13], v[124:125] op_sel:[0,0,0] op_sel_hi:[0,1,1]
	v_pk_fma_f32 v[126:127], v[152:153], v[10:11], v[126:127] op_sel:[1,0,0] op_sel_hi:[1,1,1]
	v_pk_fma_f32 v[128:129], v[152:153], v[12:13], v[128:129] op_sel:[1,0,0] op_sel_hi:[1,1,1]
	v_pk_fma_f32 v[130:131], v[180:181], v[10:11], v[130:131] op_sel:[1,0,0] op_sel_hi:[1,1,1]
	v_pk_fma_f32 v[132:133], v[180:181], v[12:13], v[132:133] op_sel:[1,0,0] op_sel_hi:[1,1,1]
	v_pk_fma_f32 v[118:119], v[140:141], v[14:15], v[118:119] op_sel:[1,0,0] op_sel_hi:[1,1,1]
	v_pk_fma_f32 v[120:121], v[140:141], v[16:17], v[120:121] op_sel:[1,0,0] op_sel_hi:[1,1,1]
	v_pk_fma_f32 v[122:123], v[148:149], v[14:15], v[122:123] op_sel:[1,0,0] op_sel_hi:[1,1,1]
	v_pk_fma_f32 v[124:125], v[148:149], v[16:17], v[124:125] op_sel:[1,0,0] op_sel_hi:[1,1,1]
	v_pk_fma_f32 v[126:127], v[154:155], v[14:15], v[126:127] op_sel:[0,0,0] op_sel_hi:[0,1,1]
	v_pk_fma_f32 v[128:129], v[154:155], v[16:17], v[128:129] op_sel:[0,0,0] op_sel_hi:[0,1,1]
	v_pk_fma_f32 v[130:131], v[0:1], v[14:15], v[130:131] op_sel:[0,0,0] op_sel_hi:[0,1,1]
	v_pk_fma_f32 v[132:133], v[0:1], v[16:17], v[132:133] op_sel:[0,0,0] op_sel_hi:[0,1,1]
	s_sub_i32 s0, s8, 0x5000
	buffer_load_dwordx4 v[34:37], v161, s[12:15], s0 offen nt
	buffer_load_dwordx4 v[2:5], v161, s[4:7], s0 offen nt
	s_sub_i32 s0, s8, 0x4c00
	buffer_load_dwordx4 v[42:45], v161, s[12:15], s0 offen nt
	buffer_load_dwordx4 v[6:9], v161, s[4:7], s0 offen nt
	s_sub_i32 s0, s8, 0x4800
	buffer_load_dwordx4 v[38:41], v161, s[12:15], s0 offen nt
	buffer_load_dwordx4 v[10:13], v161, s[4:7], s0 offen nt
	s_sub_i32 s0, s8, 0x4400
	buffer_load_dwordx4 v[46:49], v161, s[12:15], s0 offen nt
	buffer_load_dwordx4 v[14:17], v161, s[4:7], s0 offen nt
	s_sub_i32 s0, s3, 0x140
	buffer_load_dword v164, v162, s[16:19], s0 offen
	s_waitcnt vmcnt(27)
	v_pk_mul_f32 v[156:157], v[116:117], v[84:85]
	v_pk_mul_f32 v[178:179], v[116:117], v[88:89]
	v_pk_mul_f32 v[180:181], v[116:117], v[92:93]
	v_pk_mul_f32 v[238:239], v[116:117], v[96:97]
	v_pk_fma_f32 v[156:157], v[114:115], v[82:83], v[156:157]
	v_pk_fma_f32 v[178:179], v[114:115], v[86:87], v[178:179]
	v_pk_fma_f32 v[180:181], v[114:115], v[90:91], v[180:181]
	v_pk_fma_f32 v[238:239], v[114:115], v[94:95], v[238:239]
	v_add_f32_e32 v136, v156, v157
	v_add_f32_e32 v137, v178, v179
	v_add_f32_e32 v138, v180, v181
	v_add_f32_e32 v139, v238, v239
	v_pk_mul_f32 v[156:157], v[112:113], v[84:85]
	v_pk_mul_f32 v[178:179], v[112:113], v[88:89]
	v_pk_mul_f32 v[180:181], v[112:113], v[92:93]
	v_pk_mul_f32 v[238:239], v[112:113], v[96:97]
	v_pk_fma_f32 v[156:157], v[110:111], v[82:83], v[156:157]
	v_pk_fma_f32 v[178:179], v[110:111], v[86:87], v[178:179]
	v_pk_fma_f32 v[180:181], v[110:111], v[90:91], v[180:181]
	v_pk_fma_f32 v[238:239], v[110:111], v[94:95], v[238:239]
	v_add_f32_e32 v140, v156, v157
	v_add_f32_e32 v141, v178, v179
	v_add_f32_e32 v142, v180, v181
	v_add_f32_e32 v144, v238, v239
	v_pk_mul_f32 v[156:157], v[108:109], v[84:85]
	v_pk_mul_f32 v[178:179], v[108:109], v[88:89]
	v_pk_mul_f32 v[180:181], v[108:109], v[92:93]
	v_pk_mul_f32 v[238:239], v[108:109], v[96:97]
	v_pk_fma_f32 v[156:157], v[106:107], v[82:83], v[156:157]
	v_pk_fma_f32 v[178:179], v[106:107], v[86:87], v[178:179]
	v_pk_fma_f32 v[180:181], v[106:107], v[90:91], v[180:181]
	v_pk_fma_f32 v[238:239], v[106:107], v[94:95], v[238:239]
	v_add_f32_e32 v147, v156, v157
	v_add_f32_e32 v148, v178, v179
	v_add_f32_e32 v149, v180, v181
	v_add_f32_e32 v150, v238, v239
	v_pk_mul_f32 v[156:157], v[104:105], v[84:85]
	v_pk_mul_f32 v[178:179], v[104:105], v[88:89]
	v_pk_mul_f32 v[180:181], v[104:105], v[92:93]
	v_pk_mul_f32 v[238:239], v[104:105], v[96:97]
	v_pk_fma_f32 v[156:157], v[102:103], v[82:83], v[156:157]
	v_pk_fma_f32 v[178:179], v[102:103], v[86:87], v[178:179]
	v_pk_fma_f32 v[180:181], v[102:103], v[90:91], v[180:181]
	v_pk_fma_f32 v[238:239], v[102:103], v[94:95], v[238:239]
	v_add_f32_e32 v151, v156, v157
	v_add_f32_e32 v152, v178, v179
	v_add_f32_e32 v153, v180, v181
	v_add_f32_e32 v154, v238, v239
	v_mov_b32_dpp v143, v165 quad_perm:[1,2,3,3] row_mask:0xf bank_mask:0xf bound_ctrl:1
	v_add_f32_dpp v240, v165, v165 quad_perm:[1,0,3,2] row_mask:0xf bank_mask:0xf bound_ctrl:1
	v_cndmask_b32_e64 v209, v143, 0, s[28:29]
	v_add_f32_dpp v145, v165, v143 quad_perm:[2,3,3,3] row_mask:0xf bank_mask:0xf bound_ctrl:1
	v_add_f32_dpp v242, v240, v240 quad_perm:[2,3,0,1] row_mask:0xf bank_mask:0xf bound_ctrl:1
	v_add_f32_dpp v136, v136, v136 row_mirror row_mask:0xf bank_mask:0x3 bound_ctrl:1
	v_add_f32_dpp v137, v137, v137 row_mirror row_mask:0xf bank_mask:0x3 bound_ctrl:1
	v_add_f32_dpp v138, v138, v138 row_mirror row_mask:0xf bank_mask:0x3 bound_ctrl:1
	v_add_f32_dpp v139, v139, v139 row_mirror row_mask:0xf bank_mask:0x3 bound_ctrl:1
	v_add_f32_dpp v140, v140, v140 row_mirror row_mask:0xf bank_mask:0x3 bound_ctrl:1
	v_add_f32_dpp v141, v141, v141 row_mirror row_mask:0xf bank_mask:0x3 bound_ctrl:1
	v_add_f32_dpp v142, v142, v142 row_mirror row_mask:0xf bank_mask:0x3 bound_ctrl:1
	v_add_f32_dpp v144, v144, v144 row_mirror row_mask:0xf bank_mask:0x3 bound_ctrl:1
	v_add_f32_dpp v167, v165, v145 quad_perm:[3,3,3,3] row_mask:0xf bank_mask:0xf bound_ctrl:1
	v_add_f32_dpp v136, v147, v147 row_mirror row_mask:0xf bank_mask:0xc bound_ctrl:1
	v_add_f32_dpp v137, v148, v148 row_mirror row_mask:0xf bank_mask:0xc bound_ctrl:1
	v_add_f32_dpp v138, v149, v149 row_mirror row_mask:0xf bank_mask:0xc bound_ctrl:1
	v_add_f32_dpp v139, v150, v150 row_mirror row_mask:0xf bank_mask:0xc bound_ctrl:1
	v_add_f32_dpp v140, v151, v151 row_mirror row_mask:0xf bank_mask:0xc bound_ctrl:1
	v_add_f32_dpp v141, v152, v152 row_mirror row_mask:0xf bank_mask:0xc bound_ctrl:1
	v_add_f32_dpp v142, v153, v153 row_mirror row_mask:0xf bank_mask:0xc bound_ctrl:1
	v_add_f32_dpp v144, v154, v154 row_mirror row_mask:0xf bank_mask:0xc bound_ctrl:1
	v_add_f32_dpp v136, v136, v136 row_half_mirror row_mask:0xf bank_mask:0x5 bound_ctrl:1
	v_add_f32_dpp v137, v137, v137 row_half_mirror row_mask:0xf bank_mask:0x5 bound_ctrl:1
	v_add_f32_dpp v138, v138, v138 row_half_mirror row_mask:0xf bank_mask:0x5 bound_ctrl:1
	v_add_f32_dpp v139, v139, v139 row_half_mirror row_mask:0xf bank_mask:0x5 bound_ctrl:1
	v_add_f32_dpp v136, v140, v140 row_half_mirror row_mask:0xf bank_mask:0xa bound_ctrl:1
	v_add_f32_dpp v137, v141, v141 row_half_mirror row_mask:0xf bank_mask:0xa bound_ctrl:1
	v_add_f32_dpp v138, v142, v142 row_half_mirror row_mask:0xf bank_mask:0xa bound_ctrl:1
	v_add_f32_dpp v139, v144, v144 row_half_mirror row_mask:0xf bank_mask:0xa bound_ctrl:1
	v_add_f32_dpp v136, v136, v136 quad_perm:[2,3,0,1] row_mask:0xf bank_mask:0xf bound_ctrl:1
	v_add_f32_dpp v138, v138, v138 quad_perm:[2,3,0,1] row_mask:0xf bank_mask:0xf bound_ctrl:1
	v_add_f32_dpp v137, v137, v137 quad_perm:[2,3,0,1] row_mask:0xf bank_mask:0xf bound_ctrl:1
	v_add_f32_dpp v139, v139, v139 quad_perm:[2,3,0,1] row_mask:0xf bank_mask:0xf bound_ctrl:1
	v_cndmask_b32_e64 v167, v167, v145, s[28:29]
	v_cndmask_b32_e64 v172, v167, v209, s[24:25]
	v_cndmask_b32_e64 v136, v136, v138, s[24:25]
	v_cndmask_b32_e64 v137, v137, v139, s[24:25]
	v_add_f32_e32 v172, v146, v172
	v_add_f32_e32 v146, v146, v242
	v_add_f32_dpp v136, v136, v136 quad_perm:[1,0,3,2] row_mask:0xf bank_mask:0xf bound_ctrl:1
	v_add_f32_dpp v137, v137, v137 quad_perm:[1,0,3,2] row_mask:0xf bank_mask:0xf bound_ctrl:1
	v_cndmask_b32_e64 v136, v136, v137, s[28:29]
	v_fmac_f32_e32 v136, 0x3fb8aa3b, v172
	s_nop 1
	v_max_f32_dpp v179, v136, v136 quad_perm:[1,0,3,2] row_mask:0xf bank_mask:0xf bound_ctrl:1
	s_nop 1
	v_max_f32_dpp v180, v179, v179 quad_perm:[2,3,0,1] row_mask:0xf bank_mask:0xf bound_ctrl:1
	v_max_f32_e32 v180, v134, v180
	v_sub_f32_e32 v155, v134, v180
	v_sub_f32_e32 v156, v136, v180
	v_mov_b32_e32 v134, v180
	v_exp_f32_e32 v155, v155
	v_exp_f32_e32 v156, v156
	s_nop 0
	v_mov_b32_dpp v137, v155 row_newbcast:0 row_mask:0xf bank_mask:0xf
	v_mov_b32_dpp v142, v155 row_newbcast:4 row_mask:0xf bank_mask:0xf
	v_mov_b32_dpp v150, v155 row_newbcast:8 row_mask:0xf bank_mask:0xf
	v_mov_b32_dpp v178, v155 row_newbcast:12 row_mask:0xf bank_mask:0xf
	v_add_f32_dpp v157, v156, v156 quad_perm:[1,0,3,2] row_mask:0xf bank_mask:0xf bound_ctrl:1
	v_mov_b32_dpp v138, v156 row_newbcast:0 row_mask:0xf bank_mask:0xf
	v_mov_b32_dpp v139, v156 row_newbcast:1 row_mask:0xf bank_mask:0xf
	v_mov_b32_dpp v140, v156 row_newbcast:2 row_mask:0xf bank_mask:0xf
	v_mov_b32_dpp v141, v156 row_newbcast:3 row_mask:0xf bank_mask:0xf
	v_add_f32_dpp v173, v157, v157 quad_perm:[2,3,0,1] row_mask:0xf bank_mask:0xf bound_ctrl:1
	v_mov_b32_dpp v144, v156 row_newbcast:4 row_mask:0xf bank_mask:0xf
	v_mov_b32_dpp v147, v156 row_newbcast:5 row_mask:0xf bank_mask:0xf
	v_mov_b32_dpp v148, v156 row_newbcast:6 row_mask:0xf bank_mask:0xf
	v_mov_b32_dpp v149, v156 row_newbcast:7 row_mask:0xf bank_mask:0xf
	v_fma_f32 v135, v135, v155, v173
	v_mov_b32_dpp v151, v156 row_newbcast:8 row_mask:0xf bank_mask:0xf
	v_mov_b32_dpp v152, v156 row_newbcast:9 row_mask:0xf bank_mask:0xf
	v_mov_b32_dpp v153, v156 row_newbcast:10 row_mask:0xf bank_mask:0xf
	v_mov_b32_dpp v154, v156 row_newbcast:11 row_mask:0xf bank_mask:0xf
	v_mov_b32_dpp v179, v156 row_newbcast:12 row_mask:0xf bank_mask:0xf
	v_mov_b32_dpp v180, v156 row_newbcast:13 row_mask:0xf bank_mask:0xf
	v_mov_b32_dpp v181, v156 row_newbcast:14 row_mask:0xf bank_mask:0xf
	v_mov_b32_dpp v0, v156 row_newbcast:15 row_mask:0xf bank_mask:0xf
	v_pk_mul_f32 v[118:119], v[118:119], v[136:137] op_sel:[0,1] op_sel_hi:[1,1]
	v_pk_mul_f32 v[120:121], v[120:121], v[136:137] op_sel:[0,1] op_sel_hi:[1,1]
	v_pk_mul_f32 v[122:123], v[122:123], v[142:143] op_sel:[0,0] op_sel_hi:[1,0]
	v_pk_mul_f32 v[124:125], v[124:125], v[142:143] op_sel:[0,0] op_sel_hi:[1,0]
	v_pk_mul_f32 v[126:127], v[126:127], v[150:151] op_sel:[0,0] op_sel_hi:[1,0]
	v_pk_mul_f32 v[128:129], v[128:129], v[150:151] op_sel:[0,0] op_sel_hi:[1,0]
	v_pk_mul_f32 v[130:131], v[130:131], v[178:179] op_sel:[0,0] op_sel_hi:[1,0]
	v_pk_mul_f32 v[132:133], v[132:133], v[178:179] op_sel:[0,0] op_sel_hi:[1,0]
	v_pk_fma_f32 v[118:119], v[138:139], v[66:67], v[118:119] op_sel:[0,0,0] op_sel_hi:[0,1,1]
	v_pk_fma_f32 v[120:121], v[138:139], v[68:69], v[120:121] op_sel:[0,0,0] op_sel_hi:[0,1,1]
	v_pk_fma_f32 v[122:123], v[144:145], v[66:67], v[122:123] op_sel:[0,0,0] op_sel_hi:[0,1,1]
	v_pk_fma_f32 v[124:125], v[144:145], v[68:69], v[124:125] op_sel:[0,0,0] op_sel_hi:[0,1,1]
	v_pk_fma_f32 v[126:127], v[150:151], v[66:67], v[126:127] op_sel:[1,0,0] op_sel_hi:[1,1,1]
	v_pk_fma_f32 v[128:129], v[150:151], v[68:69], v[128:129] op_sel:[1,0,0] op_sel_hi:[1,1,1]
	v_pk_fma_f32 v[130:131], v[178:179], v[66:67], v[130:131] op_sel:[1,0,0] op_sel_hi:[1,1,1]
	v_pk_fma_f32 v[132:133], v[178:179], v[68:69], v[132:133] op_sel:[1,0,0] op_sel_hi:[1,1,1]
	v_pk_fma_f32 v[118:119], v[138:139], v[70:71], v[118:119] op_sel:[1,0,0] op_sel_hi:[1,1,1]
	v_pk_fma_f32 v[120:121], v[138:139], v[72:73], v[120:121] op_sel:[1,0,0] op_sel_hi:[1,1,1]
	v_pk_fma_f32 v[122:123], v[146:147], v[70:71], v[122:123] op_sel:[1,0,0] op_sel_hi:[1,1,1]
	v_pk_fma_f32 v[124:125], v[146:147], v[72:73], v[124:125] op_sel:[1,0,0] op_sel_hi:[1,1,1]
	v_pk_fma_f32 v[126:127], v[152:153], v[70:71], v[126:127] op_sel:[0,0,0] op_sel_hi:[0,1,1]
	v_pk_fma_f32 v[128:129], v[152:153], v[72:73], v[128:129] op_sel:[0,0,0] op_sel_hi:[0,1,1]
	v_pk_fma_f32 v[130:131], v[180:181], v[70:71], v[130:131] op_sel:[0,0,0] op_sel_hi:[0,1,1]
	v_pk_fma_f32 v[132:133], v[180:181], v[72:73], v[132:133] op_sel:[0,0,0] op_sel_hi:[0,1,1]
	v_pk_fma_f32 v[118:119], v[140:141], v[74:75], v[118:119] op_sel:[0,0,0] op_sel_hi:[0,1,1]
	v_pk_fma_f32 v[120:121], v[140:141], v[76:77], v[120:121] op_sel:[0,0,0] op_sel_hi:[0,1,1]
	v_pk_fma_f32 v[122:123], v[148:149], v[74:75], v[122:123] op_sel:[0,0,0] op_sel_hi:[0,1,1]
	v_pk_fma_f32 v[124:125], v[148:149], v[76:77], v[124:125] op_sel:[0,0,0] op_sel_hi:[0,1,1]
	v_pk_fma_f32 v[126:127], v[152:153], v[74:75], v[126:127] op_sel:[1,0,0] op_sel_hi:[1,1,1]
	v_pk_fma_f32 v[128:129], v[152:153], v[76:77], v[128:129] op_sel:[1,0,0] op_sel_hi:[1,1,1]
	v_pk_fma_f32 v[130:131], v[180:181], v[74:75], v[130:131] op_sel:[1,0,0] op_sel_hi:[1,1,1]
	v_pk_fma_f32 v[132:133], v[180:181], v[76:77], v[132:133] op_sel:[1,0,0] op_sel_hi:[1,1,1]
	v_pk_fma_f32 v[118:119], v[140:141], v[78:79], v[118:119] op_sel:[1,0,0] op_sel_hi:[1,1,1]
	v_pk_fma_f32 v[120:121], v[140:141], v[80:81], v[120:121] op_sel:[1,0,0] op_sel_hi:[1,1,1]
	v_pk_fma_f32 v[122:123], v[148:149], v[78:79], v[122:123] op_sel:[1,0,0] op_sel_hi:[1,1,1]
	v_pk_fma_f32 v[124:125], v[148:149], v[80:81], v[124:125] op_sel:[1,0,0] op_sel_hi:[1,1,1]
	v_pk_fma_f32 v[126:127], v[154:155], v[78:79], v[126:127] op_sel:[0,0,0] op_sel_hi:[0,1,1]
	v_pk_fma_f32 v[128:129], v[154:155], v[80:81], v[128:129] op_sel:[0,0,0] op_sel_hi:[0,1,1]
	v_pk_fma_f32 v[130:131], v[0:1], v[78:79], v[130:131] op_sel:[0,0,0] op_sel_hi:[0,1,1]
	v_pk_fma_f32 v[132:133], v[0:1], v[80:81], v[132:133] op_sel:[0,0,0] op_sel_hi:[0,1,1]
	s_sub_i32 s0, s8, 0x6000
	buffer_load_dwordx4 v[82:85], v161, s[12:15], s0 offen nt
	buffer_load_dwordx4 v[66:69], v161, s[4:7], s0 offen nt
	s_sub_i32 s0, s8, 0x5c00
	buffer_load_dwordx4 v[86:89], v161, s[12:15], s0 offen nt
	buffer_load_dwordx4 v[70:73], v161, s[4:7], s0 offen nt
	s_sub_i32 s0, s8, 0x5800
	buffer_load_dwordx4 v[90:93], v161, s[12:15], s0 offen nt
	buffer_load_dwordx4 v[74:77], v161, s[4:7], s0 offen nt
	s_sub_i32 s0, s8, 0x5400
	buffer_load_dwordx4 v[94:97], v161, s[12:15], s0 offen nt
	buffer_load_dwordx4 v[78:81], v161, s[4:7], s0 offen nt
	s_sub_i32 s0, s3, 0x180
	buffer_load_dword v165, v162, s[16:19], s0 offen
	s_waitcnt vmcnt(27)
	v_pk_mul_f32 v[156:157], v[116:117], v[212:213]
	v_pk_mul_f32 v[178:179], v[116:117], v[228:229]
	v_pk_mul_f32 v[180:181], v[116:117], v[232:233]
	v_pk_mul_f32 v[238:239], v[116:117], v[236:237]
	v_pk_fma_f32 v[156:157], v[114:115], v[210:211], v[156:157]
	v_pk_fma_f32 v[178:179], v[114:115], v[226:227], v[178:179]
	v_pk_fma_f32 v[180:181], v[114:115], v[230:231], v[180:181]
	v_pk_fma_f32 v[238:239], v[114:115], v[234:235], v[238:239]
	v_add_f32_e32 v136, v156, v157
	v_add_f32_e32 v137, v178, v179
	v_add_f32_e32 v138, v180, v181
	v_add_f32_e32 v139, v238, v239
	v_pk_mul_f32 v[156:157], v[112:113], v[212:213]
	v_pk_mul_f32 v[178:179], v[112:113], v[228:229]
	v_pk_mul_f32 v[180:181], v[112:113], v[232:233]
	v_pk_mul_f32 v[238:239], v[112:113], v[236:237]
	v_pk_fma_f32 v[156:157], v[110:111], v[210:211], v[156:157]
	v_pk_fma_f32 v[178:179], v[110:111], v[226:227], v[178:179]
	v_pk_fma_f32 v[180:181], v[110:111], v[230:231], v[180:181]
	v_pk_fma_f32 v[238:239], v[110:111], v[234:235], v[238:239]
	v_add_f32_e32 v140, v156, v157
	v_add_f32_e32 v141, v178, v179
	v_add_f32_e32 v142, v180, v181
	v_add_f32_e32 v144, v238, v239
	v_pk_mul_f32 v[156:157], v[108:109], v[212:213]
	v_pk_mul_f32 v[178:179], v[108:109], v[228:229]
	v_pk_mul_f32 v[180:181], v[108:109], v[232:233]
	v_pk_mul_f32 v[238:239], v[108:109], v[236:237]
	v_pk_fma_f32 v[156:157], v[106:107], v[210:211], v[156:157]
	v_pk_fma_f32 v[178:179], v[106:107], v[226:227], v[178:179]
	v_pk_fma_f32 v[180:181], v[106:107], v[230:231], v[180:181]
	v_pk_fma_f32 v[238:239], v[106:107], v[234:235], v[238:239]
	v_add_f32_e32 v147, v156, v157
	v_add_f32_e32 v148, v178, v179
	v_add_f32_e32 v149, v180, v181
	v_add_f32_e32 v150, v238, v239
	v_pk_mul_f32 v[156:157], v[104:105], v[212:213]
	v_pk_mul_f32 v[178:179], v[104:105], v[228:229]
	v_pk_mul_f32 v[180:181], v[104:105], v[232:233]
	v_pk_mul_f32 v[238:239], v[104:105], v[236:237]
	v_pk_fma_f32 v[156:157], v[102:103], v[210:211], v[156:157]
	v_pk_fma_f32 v[178:179], v[102:103], v[226:227], v[178:179]
	v_pk_fma_f32 v[180:181], v[102:103], v[230:231], v[180:181]
	v_pk_fma_f32 v[238:239], v[102:103], v[234:235], v[238:239]
	v_add_f32_e32 v151, v156, v157
	v_add_f32_e32 v152, v178, v179
	v_add_f32_e32 v153, v180, v181
	v_add_f32_e32 v154, v238, v239
	v_mov_b32_dpp v143, v166 quad_perm:[1,2,3,3] row_mask:0xf bank_mask:0xf bound_ctrl:1
	v_add_f32_dpp v240, v166, v166 quad_perm:[1,0,3,2] row_mask:0xf bank_mask:0xf bound_ctrl:1
	v_cndmask_b32_e64 v209, v143, 0, s[28:29]
	v_add_f32_dpp v145, v166, v143 quad_perm:[2,3,3,3] row_mask:0xf bank_mask:0xf bound_ctrl:1
	v_add_f32_dpp v242, v240, v240 quad_perm:[2,3,0,1] row_mask:0xf bank_mask:0xf bound_ctrl:1
	v_add_f32_dpp v136, v136, v136 row_mirror row_mask:0xf bank_mask:0x3 bound_ctrl:1
	v_add_f32_dpp v137, v137, v137 row_mirror row_mask:0xf bank_mask:0x3 bound_ctrl:1
	v_add_f32_dpp v138, v138, v138 row_mirror row_mask:0xf bank_mask:0x3 bound_ctrl:1
	v_add_f32_dpp v139, v139, v139 row_mirror row_mask:0xf bank_mask:0x3 bound_ctrl:1
	v_add_f32_dpp v140, v140, v140 row_mirror row_mask:0xf bank_mask:0x3 bound_ctrl:1
	v_add_f32_dpp v141, v141, v141 row_mirror row_mask:0xf bank_mask:0x3 bound_ctrl:1
	v_add_f32_dpp v142, v142, v142 row_mirror row_mask:0xf bank_mask:0x3 bound_ctrl:1
	v_add_f32_dpp v144, v144, v144 row_mirror row_mask:0xf bank_mask:0x3 bound_ctrl:1
	v_add_f32_dpp v167, v166, v145 quad_perm:[3,3,3,3] row_mask:0xf bank_mask:0xf bound_ctrl:1
	v_add_f32_dpp v136, v147, v147 row_mirror row_mask:0xf bank_mask:0xc bound_ctrl:1
	v_add_f32_dpp v137, v148, v148 row_mirror row_mask:0xf bank_mask:0xc bound_ctrl:1
	v_add_f32_dpp v138, v149, v149 row_mirror row_mask:0xf bank_mask:0xc bound_ctrl:1
	v_add_f32_dpp v139, v150, v150 row_mirror row_mask:0xf bank_mask:0xc bound_ctrl:1
	v_add_f32_dpp v140, v151, v151 row_mirror row_mask:0xf bank_mask:0xc bound_ctrl:1
	v_add_f32_dpp v141, v152, v152 row_mirror row_mask:0xf bank_mask:0xc bound_ctrl:1
	v_add_f32_dpp v142, v153, v153 row_mirror row_mask:0xf bank_mask:0xc bound_ctrl:1
	v_add_f32_dpp v144, v154, v154 row_mirror row_mask:0xf bank_mask:0xc bound_ctrl:1
	v_add_f32_dpp v136, v136, v136 row_half_mirror row_mask:0xf bank_mask:0x5 bound_ctrl:1
	v_add_f32_dpp v137, v137, v137 row_half_mirror row_mask:0xf bank_mask:0x5 bound_ctrl:1
	v_add_f32_dpp v138, v138, v138 row_half_mirror row_mask:0xf bank_mask:0x5 bound_ctrl:1
	v_add_f32_dpp v139, v139, v139 row_half_mirror row_mask:0xf bank_mask:0x5 bound_ctrl:1
	v_add_f32_dpp v136, v140, v140 row_half_mirror row_mask:0xf bank_mask:0xa bound_ctrl:1
	v_add_f32_dpp v137, v141, v141 row_half_mirror row_mask:0xf bank_mask:0xa bound_ctrl:1
	v_add_f32_dpp v138, v142, v142 row_half_mirror row_mask:0xf bank_mask:0xa bound_ctrl:1
	v_add_f32_dpp v139, v144, v144 row_half_mirror row_mask:0xf bank_mask:0xa bound_ctrl:1
	v_add_f32_dpp v136, v136, v136 quad_perm:[2,3,0,1] row_mask:0xf bank_mask:0xf bound_ctrl:1
	v_add_f32_dpp v138, v138, v138 quad_perm:[2,3,0,1] row_mask:0xf bank_mask:0xf bound_ctrl:1
	v_add_f32_dpp v137, v137, v137 quad_perm:[2,3,0,1] row_mask:0xf bank_mask:0xf bound_ctrl:1
	v_add_f32_dpp v139, v139, v139 quad_perm:[2,3,0,1] row_mask:0xf bank_mask:0xf bound_ctrl:1
	v_cndmask_b32_e64 v167, v167, v145, s[28:29]
	v_cndmask_b32_e64 v172, v167, v209, s[24:25]
	v_cndmask_b32_e64 v136, v136, v138, s[24:25]
	v_cndmask_b32_e64 v137, v137, v139, s[24:25]
	v_add_f32_e32 v172, v146, v172
	v_add_f32_e32 v146, v146, v242
	v_add_f32_dpp v136, v136, v136 quad_perm:[1,0,3,2] row_mask:0xf bank_mask:0xf bound_ctrl:1
	v_add_f32_dpp v137, v137, v137 quad_perm:[1,0,3,2] row_mask:0xf bank_mask:0xf bound_ctrl:1
	v_cndmask_b32_e64 v136, v136, v137, s[28:29]
	v_fmac_f32_e32 v136, 0x3fb8aa3b, v172
	s_nop 1
	v_max_f32_dpp v179, v136, v136 quad_perm:[1,0,3,2] row_mask:0xf bank_mask:0xf bound_ctrl:1
	s_nop 1
	v_max_f32_dpp v180, v179, v179 quad_perm:[2,3,0,1] row_mask:0xf bank_mask:0xf bound_ctrl:1
	v_max_f32_e32 v180, v134, v180
	v_sub_f32_e32 v155, v134, v180
	v_sub_f32_e32 v156, v136, v180
	v_mov_b32_e32 v134, v180
	v_exp_f32_e32 v155, v155
	v_exp_f32_e32 v156, v156
	s_nop 0
	v_mov_b32_dpp v137, v155 row_newbcast:0 row_mask:0xf bank_mask:0xf
	v_mov_b32_dpp v142, v155 row_newbcast:4 row_mask:0xf bank_mask:0xf
	v_mov_b32_dpp v150, v155 row_newbcast:8 row_mask:0xf bank_mask:0xf
	v_mov_b32_dpp v178, v155 row_newbcast:12 row_mask:0xf bank_mask:0xf
	v_add_f32_dpp v157, v156, v156 quad_perm:[1,0,3,2] row_mask:0xf bank_mask:0xf bound_ctrl:1
	v_mov_b32_dpp v138, v156 row_newbcast:0 row_mask:0xf bank_mask:0xf
	v_mov_b32_dpp v139, v156 row_newbcast:1 row_mask:0xf bank_mask:0xf
	v_mov_b32_dpp v140, v156 row_newbcast:2 row_mask:0xf bank_mask:0xf
	v_mov_b32_dpp v141, v156 row_newbcast:3 row_mask:0xf bank_mask:0xf
	v_add_f32_dpp v173, v157, v157 quad_perm:[2,3,0,1] row_mask:0xf bank_mask:0xf bound_ctrl:1
	v_mov_b32_dpp v144, v156 row_newbcast:4 row_mask:0xf bank_mask:0xf
	v_mov_b32_dpp v147, v156 row_newbcast:5 row_mask:0xf bank_mask:0xf
	v_mov_b32_dpp v148, v156 row_newbcast:6 row_mask:0xf bank_mask:0xf
	v_mov_b32_dpp v149, v156 row_newbcast:7 row_mask:0xf bank_mask:0xf
	v_fma_f32 v135, v135, v155, v173
	v_mov_b32_dpp v151, v156 row_newbcast:8 row_mask:0xf bank_mask:0xf
	v_mov_b32_dpp v152, v156 row_newbcast:9 row_mask:0xf bank_mask:0xf
	v_mov_b32_dpp v153, v156 row_newbcast:10 row_mask:0xf bank_mask:0xf
	v_mov_b32_dpp v154, v156 row_newbcast:11 row_mask:0xf bank_mask:0xf
	v_mov_b32_dpp v179, v156 row_newbcast:12 row_mask:0xf bank_mask:0xf
	v_mov_b32_dpp v180, v156 row_newbcast:13 row_mask:0xf bank_mask:0xf
	v_mov_b32_dpp v181, v156 row_newbcast:14 row_mask:0xf bank_mask:0xf
	v_mov_b32_dpp v0, v156 row_newbcast:15 row_mask:0xf bank_mask:0xf
	v_pk_mul_f32 v[118:119], v[118:119], v[136:137] op_sel:[0,1] op_sel_hi:[1,1]
	v_pk_mul_f32 v[120:121], v[120:121], v[136:137] op_sel:[0,1] op_sel_hi:[1,1]
	v_pk_mul_f32 v[122:123], v[122:123], v[142:143] op_sel:[0,0] op_sel_hi:[1,0]
	v_pk_mul_f32 v[124:125], v[124:125], v[142:143] op_sel:[0,0] op_sel_hi:[1,0]
	v_pk_mul_f32 v[126:127], v[126:127], v[150:151] op_sel:[0,0] op_sel_hi:[1,0]
	v_pk_mul_f32 v[128:129], v[128:129], v[150:151] op_sel:[0,0] op_sel_hi:[1,0]
	v_pk_mul_f32 v[130:131], v[130:131], v[178:179] op_sel:[0,0] op_sel_hi:[1,0]
	v_pk_mul_f32 v[132:133], v[132:133], v[178:179] op_sel:[0,0] op_sel_hi:[1,0]
	v_pk_fma_f32 v[118:119], v[138:139], v[250:251], v[118:119] op_sel:[0,0,0] op_sel_hi:[0,1,1]
	v_pk_fma_f32 v[120:121], v[138:139], v[252:253], v[120:121] op_sel:[0,0,0] op_sel_hi:[0,1,1]
	v_pk_fma_f32 v[122:123], v[144:145], v[250:251], v[122:123] op_sel:[0,0,0] op_sel_hi:[0,1,1]
	v_pk_fma_f32 v[124:125], v[144:145], v[252:253], v[124:125] op_sel:[0,0,0] op_sel_hi:[0,1,1]
	v_pk_fma_f32 v[126:127], v[150:151], v[250:251], v[126:127] op_sel:[1,0,0] op_sel_hi:[1,1,1]
	v_pk_fma_f32 v[128:129], v[150:151], v[252:253], v[128:129] op_sel:[1,0,0] op_sel_hi:[1,1,1]
	v_pk_fma_f32 v[130:131], v[178:179], v[250:251], v[130:131] op_sel:[1,0,0] op_sel_hi:[1,1,1]
	v_pk_fma_f32 v[132:133], v[178:179], v[252:253], v[132:133] op_sel:[1,0,0] op_sel_hi:[1,1,1]
	v_pk_fma_f32 v[118:119], v[138:139], v[98:99], v[118:119] op_sel:[1,0,0] op_sel_hi:[1,1,1]
	v_pk_fma_f32 v[120:121], v[138:139], v[100:101], v[120:121] op_sel:[1,0,0] op_sel_hi:[1,1,1]
	v_pk_fma_f32 v[122:123], v[146:147], v[98:99], v[122:123] op_sel:[1,0,0] op_sel_hi:[1,1,1]
	v_pk_fma_f32 v[124:125], v[146:147], v[100:101], v[124:125] op_sel:[1,0,0] op_sel_hi:[1,1,1]
	v_pk_fma_f32 v[126:127], v[152:153], v[98:99], v[126:127] op_sel:[0,0,0] op_sel_hi:[0,1,1]
	v_pk_fma_f32 v[128:129], v[152:153], v[100:101], v[128:129] op_sel:[0,0,0] op_sel_hi:[0,1,1]
	v_pk_fma_f32 v[130:131], v[180:181], v[98:99], v[130:131] op_sel:[0,0,0] op_sel_hi:[0,1,1]
	v_pk_fma_f32 v[132:133], v[180:181], v[100:101], v[132:133] op_sel:[0,0,0] op_sel_hi:[0,1,1]
	v_pk_fma_f32 v[118:119], v[140:141], v[174:175], v[118:119] op_sel:[0,0,0] op_sel_hi:[0,1,1]
	v_pk_fma_f32 v[120:121], v[140:141], v[176:177], v[120:121] op_sel:[0,0,0] op_sel_hi:[0,1,1]
	v_pk_fma_f32 v[122:123], v[148:149], v[174:175], v[122:123] op_sel:[0,0,0] op_sel_hi:[0,1,1]
	v_pk_fma_f32 v[124:125], v[148:149], v[176:177], v[124:125] op_sel:[0,0,0] op_sel_hi:[0,1,1]
	v_pk_fma_f32 v[126:127], v[152:153], v[174:175], v[126:127] op_sel:[1,0,0] op_sel_hi:[1,1,1]
	v_pk_fma_f32 v[128:129], v[152:153], v[176:177], v[128:129] op_sel:[1,0,0] op_sel_hi:[1,1,1]
	v_pk_fma_f32 v[130:131], v[180:181], v[174:175], v[130:131] op_sel:[1,0,0] op_sel_hi:[1,1,1]
	v_pk_fma_f32 v[132:133], v[180:181], v[176:177], v[132:133] op_sel:[1,0,0] op_sel_hi:[1,1,1]
	v_pk_fma_f32 v[118:119], v[140:141], v[168:169], v[118:119] op_sel:[1,0,0] op_sel_hi:[1,1,1]
	v_pk_fma_f32 v[120:121], v[140:141], v[170:171], v[120:121] op_sel:[1,0,0] op_sel_hi:[1,1,1]
	v_pk_fma_f32 v[122:123], v[148:149], v[168:169], v[122:123] op_sel:[1,0,0] op_sel_hi:[1,1,1]
	v_pk_fma_f32 v[124:125], v[148:149], v[170:171], v[124:125] op_sel:[1,0,0] op_sel_hi:[1,1,1]
	v_pk_fma_f32 v[126:127], v[154:155], v[168:169], v[126:127] op_sel:[0,0,0] op_sel_hi:[0,1,1]
	v_pk_fma_f32 v[128:129], v[154:155], v[170:171], v[128:129] op_sel:[0,0,0] op_sel_hi:[0,1,1]
	v_pk_fma_f32 v[130:131], v[0:1], v[168:169], v[130:131] op_sel:[0,0,0] op_sel_hi:[0,1,1]
	v_pk_fma_f32 v[132:133], v[0:1], v[170:171], v[132:133] op_sel:[0,0,0] op_sel_hi:[0,1,1]
	s_sub_i32 s0, s8, 0x7000
	buffer_load_dwordx4 v[210:213], v161, s[12:15], s0 offen nt
	buffer_load_dwordx4 v[250:253], v161, s[4:7], s0 offen nt
	s_sub_i32 s0, s8, 0x6c00
	buffer_load_dwordx4 v[226:229], v161, s[12:15], s0 offen nt
	buffer_load_dwordx4 v[98:101], v161, s[4:7], s0 offen nt
	s_sub_i32 s0, s8, 0x6800
	buffer_load_dwordx4 v[230:233], v161, s[12:15], s0 offen nt
	buffer_load_dwordx4 v[174:177], v161, s[4:7], s0 offen nt
	s_sub_i32 s0, s8, 0x6400
	buffer_load_dwordx4 v[234:237], v161, s[12:15], s0 offen nt
	buffer_load_dwordx4 v[168:171], v161, s[4:7], s0 offen nt
	s_sub_i32 s0, s3, 0x1c0
	buffer_load_dword v166, v162, s[16:19], s0 offen
	s_sub_i32 s8, s8, 0x4000
	s_sub_i32 s3, s3, 0x100
	s_sub_i32 s2, s2, 1
	s_cmp_lg_u32 s2, 0
	s_cbranch_scc1 .Lpg_loop
	s_waitcnt vmcnt(27)
	v_pk_mul_f32 v[156:157], v[116:117], v[52:53]
	v_pk_mul_f32 v[178:179], v[116:117], v[60:61]
	v_pk_mul_f32 v[180:181], v[116:117], v[56:57]
	v_pk_mul_f32 v[238:239], v[116:117], v[64:65]
	v_pk_fma_f32 v[156:157], v[114:115], v[50:51], v[156:157]
	v_pk_fma_f32 v[178:179], v[114:115], v[58:59], v[178:179]
	v_pk_fma_f32 v[180:181], v[114:115], v[54:55], v[180:181]
	v_pk_fma_f32 v[238:239], v[114:115], v[62:63], v[238:239]
	v_add_f32_e32 v136, v156, v157
	v_add_f32_e32 v137, v178, v179
	v_add_f32_e32 v138, v180, v181
	v_add_f32_e32 v139, v238, v239
	v_pk_mul_f32 v[156:157], v[112:113], v[52:53]
	v_pk_mul_f32 v[178:179], v[112:113], v[60:61]
	v_pk_mul_f32 v[180:181], v[112:113], v[56:57]
	v_pk_mul_f32 v[238:239], v[112:113], v[64:65]
	v_pk_fma_f32 v[156:157], v[110:111], v[50:51], v[156:157]
	v_pk_fma_f32 v[178:179], v[110:111], v[58:59], v[178:179]
	v_pk_fma_f32 v[180:181], v[110:111], v[54:55], v[180:181]
	v_pk_fma_f32 v[238:239], v[110:111], v[62:63], v[238:239]
	v_add_f32_e32 v140, v156, v157
	v_add_f32_e32 v141, v178, v179
	v_add_f32_e32 v142, v180, v181
	v_add_f32_e32 v144, v238, v239
	v_pk_mul_f32 v[156:157], v[108:109], v[52:53]
	v_pk_mul_f32 v[178:179], v[108:109], v[60:61]
	v_pk_mul_f32 v[180:181], v[108:109], v[56:57]
	v_pk_mul_f32 v[238:239], v[108:109], v[64:65]
	v_pk_fma_f32 v[156:157], v[106:107], v[50:51], v[156:157]
	v_pk_fma_f32 v[178:179], v[106:107], v[58:59], v[178:179]
	v_pk_fma_f32 v[180:181], v[106:107], v[54:55], v[180:181]
	v_pk_fma_f32 v[238:239], v[106:107], v[62:63], v[238:239]
	v_add_f32_e32 v147, v156, v157
	v_add_f32_e32 v148, v178, v179
	v_add_f32_e32 v149, v180, v181
	v_add_f32_e32 v150, v238, v239
	v_pk_mul_f32 v[156:157], v[104:105], v[52:53]
	v_pk_mul_f32 v[178:179], v[104:105], v[60:61]
	v_pk_mul_f32 v[180:181], v[104:105], v[56:57]
	v_pk_mul_f32 v[238:239], v[104:105], v[64:65]
	v_pk_fma_f32 v[156:157], v[102:103], v[50:51], v[156:157]
	v_pk_fma_f32 v[178:179], v[102:103], v[58:59], v[178:179]
	v_pk_fma_f32 v[180:181], v[102:103], v[54:55], v[180:181]
	v_pk_fma_f32 v[238:239], v[102:103], v[62:63], v[238:239]
	v_add_f32_e32 v151, v156, v157
	v_add_f32_e32 v152, v178, v179
	v_add_f32_e32 v153, v180, v181
	v_add_f32_e32 v154, v238, v239
	v_mov_b32_dpp v143, v163 quad_perm:[1,2,3,3] row_mask:0xf bank_mask:0xf bound_ctrl:1
	v_add_f32_dpp v240, v163, v163 quad_perm:[1,0,3,2] row_mask:0xf bank_mask:0xf bound_ctrl:1
	v_cndmask_b32_e64 v209, v143, 0, s[28:29]
	v_add_f32_dpp v145, v163, v143 quad_perm:[2,3,3,3] row_mask:0xf bank_mask:0xf bound_ctrl:1
	v_add_f32_dpp v242, v240, v240 quad_perm:[2,3,0,1] row_mask:0xf bank_mask:0xf bound_ctrl:1
	v_add_f32_dpp v136, v136, v136 row_mirror row_mask:0xf bank_mask:0x3 bound_ctrl:1
	v_add_f32_dpp v137, v137, v137 row_mirror row_mask:0xf bank_mask:0x3 bound_ctrl:1
	v_add_f32_dpp v138, v138, v138 row_mirror row_mask:0xf bank_mask:0x3 bound_ctrl:1
	v_add_f32_dpp v139, v139, v139 row_mirror row_mask:0xf bank_mask:0x3 bound_ctrl:1
	v_add_f32_dpp v140, v140, v140 row_mirror row_mask:0xf bank_mask:0x3 bound_ctrl:1
	v_add_f32_dpp v141, v141, v141 row_mirror row_mask:0xf bank_mask:0x3 bound_ctrl:1
	v_add_f32_dpp v142, v142, v142 row_mirror row_mask:0xf bank_mask:0x3 bound_ctrl:1
	v_add_f32_dpp v144, v144, v144 row_mirror row_mask:0xf bank_mask:0x3 bound_ctrl:1
	v_add_f32_dpp v167, v163, v145 quad_perm:[3,3,3,3] row_mask:0xf bank_mask:0xf bound_ctrl:1
	v_add_f32_dpp v136, v147, v147 row_mirror row_mask:0xf bank_mask:0xc bound_ctrl:1
	v_add_f32_dpp v137, v148, v148 row_mirror row_mask:0xf bank_mask:0xc bound_ctrl:1
	v_add_f32_dpp v138, v149, v149 row_mirror row_mask:0xf bank_mask:0xc bound_ctrl:1
	v_add_f32_dpp v139, v150, v150 row_mirror row_mask:0xf bank_mask:0xc bound_ctrl:1
	v_add_f32_dpp v140, v151, v151 row_mirror row_mask:0xf bank_mask:0xc bound_ctrl:1
	v_add_f32_dpp v141, v152, v152 row_mirror row_mask:0xf bank_mask:0xc bound_ctrl:1
	v_add_f32_dpp v142, v153, v153 row_mirror row_mask:0xf bank_mask:0xc bound_ctrl:1
	v_add_f32_dpp v144, v154, v154 row_mirror row_mask:0xf bank_mask:0xc bound_ctrl:1
	v_add_f32_dpp v136, v136, v136 row_half_mirror row_mask:0xf bank_mask:0x5 bound_ctrl:1
	v_add_f32_dpp v137, v137, v137 row_half_mirror row_mask:0xf bank_mask:0x5 bound_ctrl:1
	v_add_f32_dpp v138, v138, v138 row_half_mirror row_mask:0xf bank_mask:0x5 bound_ctrl:1
	v_add_f32_dpp v139, v139, v139 row_half_mirror row_mask:0xf bank_mask:0x5 bound_ctrl:1
	v_add_f32_dpp v136, v140, v140 row_half_mirror row_mask:0xf bank_mask:0xa bound_ctrl:1
	v_add_f32_dpp v137, v141, v141 row_half_mirror row_mask:0xf bank_mask:0xa bound_ctrl:1
	v_add_f32_dpp v138, v142, v142 row_half_mirror row_mask:0xf bank_mask:0xa bound_ctrl:1
	v_add_f32_dpp v139, v144, v144 row_half_mirror row_mask:0xf bank_mask:0xa bound_ctrl:1
	v_add_f32_dpp v136, v136, v136 quad_perm:[2,3,0,1] row_mask:0xf bank_mask:0xf bound_ctrl:1
	v_add_f32_dpp v138, v138, v138 quad_perm:[2,3,0,1] row_mask:0xf bank_mask:0xf bound_ctrl:1
	v_add_f32_dpp v137, v137, v137 quad_perm:[2,3,0,1] row_mask:0xf bank_mask:0xf bound_ctrl:1
	v_add_f32_dpp v139, v139, v139 quad_perm:[2,3,0,1] row_mask:0xf bank_mask:0xf bound_ctrl:1
	v_cndmask_b32_e64 v167, v167, v145, s[28:29]
	v_cndmask_b32_e64 v172, v167, v209, s[24:25]
	v_cndmask_b32_e64 v136, v136, v138, s[24:25]
	v_cndmask_b32_e64 v137, v137, v139, s[24:25]
	v_add_f32_e32 v172, v146, v172
	v_add_f32_e32 v146, v146, v242
	v_add_f32_dpp v136, v136, v136 quad_perm:[1,0,3,2] row_mask:0xf bank_mask:0xf bound_ctrl:1
	v_add_f32_dpp v137, v137, v137 quad_perm:[1,0,3,2] row_mask:0xf bank_mask:0xf bound_ctrl:1
	v_cndmask_b32_e64 v136, v136, v137, s[28:29]
	v_fmac_f32_e32 v136, 0x3fb8aa3b, v172
	s_nop 1
	v_max_f32_dpp v179, v136, v136 quad_perm:[1,0,3,2] row_mask:0xf bank_mask:0xf bound_ctrl:1
	s_nop 1
	v_max_f32_dpp v180, v179, v179 quad_perm:[2,3,0,1] row_mask:0xf bank_mask:0xf bound_ctrl:1
	v_max_f32_e32 v180, v134, v180
	v_sub_f32_e32 v155, v134, v180
	v_sub_f32_e32 v156, v136, v180
	v_mov_b32_e32 v134, v180
	v_exp_f32_e32 v155, v155
	v_exp_f32_e32 v156, v156
	s_nop 0
	v_mov_b32_dpp v137, v155 row_newbcast:0 row_mask:0xf bank_mask:0xf
	v_mov_b32_dpp v142, v155 row_newbcast:4 row_mask:0xf bank_mask:0xf
	v_mov_b32_dpp v150, v155 row_newbcast:8 row_mask:0xf bank_mask:0xf
	v_mov_b32_dpp v178, v155 row_newbcast:12 row_mask:0xf bank_mask:0xf
	v_add_f32_dpp v157, v156, v156 quad_perm:[1,0,3,2] row_mask:0xf bank_mask:0xf bound_ctrl:1
	v_mov_b32_dpp v138, v156 row_newbcast:0 row_mask:0xf bank_mask:0xf
	v_mov_b32_dpp v139, v156 row_newbcast:1 row_mask:0xf bank_mask:0xf
	v_mov_b32_dpp v140, v156 row_newbcast:2 row_mask:0xf bank_mask:0xf
	v_mov_b32_dpp v141, v156 row_newbcast:3 row_mask:0xf bank_mask:0xf
	v_add_f32_dpp v173, v157, v157 quad_perm:[2,3,0,1] row_mask:0xf bank_mask:0xf bound_ctrl:1
	v_mov_b32_dpp v144, v156 row_newbcast:4 row_mask:0xf bank_mask:0xf
	v_mov_b32_dpp v147, v156 row_newbcast:5 row_mask:0xf bank_mask:0xf
	v_mov_b32_dpp v148, v156 row_newbcast:6 row_mask:0xf bank_mask:0xf
	v_mov_b32_dpp v149, v156 row_newbcast:7 row_mask:0xf bank_mask:0xf
	v_fma_f32 v135, v135, v155, v173
	v_mov_b32_dpp v151, v156 row_newbcast:8 row_mask:0xf bank_mask:0xf
	v_mov_b32_dpp v152, v156 row_newbcast:9 row_mask:0xf bank_mask:0xf
	v_mov_b32_dpp v153, v156 row_newbcast:10 row_mask:0xf bank_mask:0xf
	v_mov_b32_dpp v154, v156 row_newbcast:11 row_mask:0xf bank_mask:0xf
	v_mov_b32_dpp v179, v156 row_newbcast:12 row_mask:0xf bank_mask:0xf
	v_mov_b32_dpp v180, v156 row_newbcast:13 row_mask:0xf bank_mask:0xf
	v_mov_b32_dpp v181, v156 row_newbcast:14 row_mask:0xf bank_mask:0xf
	v_mov_b32_dpp v0, v156 row_newbcast:15 row_mask:0xf bank_mask:0xf
	v_pk_mul_f32 v[118:119], v[118:119], v[136:137] op_sel:[0,1] op_sel_hi:[1,1]
	v_pk_mul_f32 v[120:121], v[120:121], v[136:137] op_sel:[0,1] op_sel_hi:[1,1]
	v_pk_mul_f32 v[122:123], v[122:123], v[142:143] op_sel:[0,0] op_sel_hi:[1,0]
	v_pk_mul_f32 v[124:125], v[124:125], v[142:143] op_sel:[0,0] op_sel_hi:[1,0]
	v_pk_mul_f32 v[126:127], v[126:127], v[150:151] op_sel:[0,0] op_sel_hi:[1,0]
	v_pk_mul_f32 v[128:129], v[128:129], v[150:151] op_sel:[0,0] op_sel_hi:[1,0]
	v_pk_mul_f32 v[130:131], v[130:131], v[178:179] op_sel:[0,0] op_sel_hi:[1,0]
	v_pk_mul_f32 v[132:133], v[132:133], v[178:179] op_sel:[0,0] op_sel_hi:[1,0]
	v_pk_fma_f32 v[118:119], v[138:139], v[22:23], v[118:119] op_sel:[0,0,0] op_sel_hi:[0,1,1]
	v_pk_fma_f32 v[120:121], v[138:139], v[24:25], v[120:121] op_sel:[0,0,0] op_sel_hi:[0,1,1]
	v_pk_fma_f32 v[122:123], v[144:145], v[22:23], v[122:123] op_sel:[0,0,0] op_sel_hi:[0,1,1]
	v_pk_fma_f32 v[124:125], v[144:145], v[24:25], v[124:125] op_sel:[0,0,0] op_sel_hi:[0,1,1]
	v_pk_fma_f32 v[126:127], v[150:151], v[22:23], v[126:127] op_sel:[1,0,0] op_sel_hi:[1,1,1]
	v_pk_fma_f32 v[128:129], v[150:151], v[24:25], v[128:129] op_sel:[1,0,0] op_sel_hi:[1,1,1]
	v_pk_fma_f32 v[130:131], v[178:179], v[22:23], v[130:131] op_sel:[1,0,0] op_sel_hi:[1,1,1]
	v_pk_fma_f32 v[132:133], v[178:179], v[24:25], v[132:133] op_sel:[1,0,0] op_sel_hi:[1,1,1]
	v_pk_fma_f32 v[118:119], v[138:139], v[18:19], v[118:119] op_sel:[1,0,0] op_sel_hi:[1,1,1]
	v_pk_fma_f32 v[120:121], v[138:139], v[20:21], v[120:121] op_sel:[1,0,0] op_sel_hi:[1,1,1]
	v_pk_fma_f32 v[122:123], v[146:147], v[18:19], v[122:123] op_sel:[1,0,0] op_sel_hi:[1,1,1]
	v_pk_fma_f32 v[124:125], v[146:147], v[20:21], v[124:125] op_sel:[1,0,0] op_sel_hi:[1,1,1]
	v_pk_fma_f32 v[126:127], v[152:153], v[18:19], v[126:127] op_sel:[0,0,0] op_sel_hi:[0,1,1]
	v_pk_fma_f32 v[128:129], v[152:153], v[20:21], v[128:129] op_sel:[0,0,0] op_sel_hi:[0,1,1]
	v_pk_fma_f32 v[130:131], v[180:181], v[18:19], v[130:131] op_sel:[0,0,0] op_sel_hi:[0,1,1]
	v_pk_fma_f32 v[132:133], v[180:181], v[20:21], v[132:133] op_sel:[0,0,0] op_sel_hi:[0,1,1]
	v_pk_fma_f32 v[118:119], v[140:141], v[26:27], v[118:119] op_sel:[0,0,0] op_sel_hi:[0,1,1]
	v_pk_fma_f32 v[120:121], v[140:141], v[28:29], v[120:121] op_sel:[0,0,0] op_sel_hi:[0,1,1]
	v_pk_fma_f32 v[122:123], v[148:149], v[26:27], v[122:123] op_sel:[0,0,0] op_sel_hi:[0,1,1]
	v_pk_fma_f32 v[124:125], v[148:149], v[28:29], v[124:125] op_sel:[0,0,0] op_sel_hi:[0,1,1]
	v_pk_fma_f32 v[126:127], v[152:153], v[26:27], v[126:127] op_sel:[1,0,0] op_sel_hi:[1,1,1]
	v_pk_fma_f32 v[128:129], v[152:153], v[28:29], v[128:129] op_sel:[1,0,0] op_sel_hi:[1,1,1]
	v_pk_fma_f32 v[130:131], v[180:181], v[26:27], v[130:131] op_sel:[1,0,0] op_sel_hi:[1,1,1]
	v_pk_fma_f32 v[132:133], v[180:181], v[28:29], v[132:133] op_sel:[1,0,0] op_sel_hi:[1,1,1]
	v_pk_fma_f32 v[118:119], v[140:141], v[30:31], v[118:119] op_sel:[1,0,0] op_sel_hi:[1,1,1]
	v_pk_fma_f32 v[120:121], v[140:141], v[32:33], v[120:121] op_sel:[1,0,0] op_sel_hi:[1,1,1]
	v_pk_fma_f32 v[122:123], v[148:149], v[30:31], v[122:123] op_sel:[1,0,0] op_sel_hi:[1,1,1]
	v_pk_fma_f32 v[124:125], v[148:149], v[32:33], v[124:125] op_sel:[1,0,0] op_sel_hi:[1,1,1]
	v_pk_fma_f32 v[126:127], v[154:155], v[30:31], v[126:127] op_sel:[0,0,0] op_sel_hi:[0,1,1]
	v_pk_fma_f32 v[128:129], v[154:155], v[32:33], v[128:129] op_sel:[0,0,0] op_sel_hi:[0,1,1]
	v_pk_fma_f32 v[130:131], v[0:1], v[30:31], v[130:131] op_sel:[0,0,0] op_sel_hi:[0,1,1]
	v_pk_fma_f32 v[132:133], v[0:1], v[32:33], v[132:133] op_sel:[0,0,0] op_sel_hi:[0,1,1]
	s_waitcnt vmcnt(18)
	v_pk_mul_f32 v[156:157], v[116:117], v[36:37]
	v_pk_mul_f32 v[178:179], v[116:117], v[44:45]
	v_pk_mul_f32 v[180:181], v[116:117], v[40:41]
	v_pk_mul_f32 v[238:239], v[116:117], v[48:49]
	v_pk_fma_f32 v[156:157], v[114:115], v[34:35], v[156:157]
	v_pk_fma_f32 v[178:179], v[114:115], v[42:43], v[178:179]
	v_pk_fma_f32 v[180:181], v[114:115], v[38:39], v[180:181]
	v_pk_fma_f32 v[238:239], v[114:115], v[46:47], v[238:239]
	v_add_f32_e32 v136, v156, v157
	v_add_f32_e32 v137, v178, v179
	v_add_f32_e32 v138, v180, v181
	v_add_f32_e32 v139, v238, v239
	v_pk_mul_f32 v[156:157], v[112:113], v[36:37]
	v_pk_mul_f32 v[178:179], v[112:113], v[44:45]
	v_pk_mul_f32 v[180:181], v[112:113], v[40:41]
	v_pk_mul_f32 v[238:239], v[112:113], v[48:49]
	v_pk_fma_f32 v[156:157], v[110:111], v[34:35], v[156:157]
	v_pk_fma_f32 v[178:179], v[110:111], v[42:43], v[178:179]
	v_pk_fma_f32 v[180:181], v[110:111], v[38:39], v[180:181]
	v_pk_fma_f32 v[238:239], v[110:111], v[46:47], v[238:239]
	v_add_f32_e32 v140, v156, v157
	v_add_f32_e32 v141, v178, v179
	v_add_f32_e32 v142, v180, v181
	v_add_f32_e32 v144, v238, v239
	v_pk_mul_f32 v[156:157], v[108:109], v[36:37]
	v_pk_mul_f32 v[178:179], v[108:109], v[44:45]
	v_pk_mul_f32 v[180:181], v[108:109], v[40:41]
	v_pk_mul_f32 v[238:239], v[108:109], v[48:49]
	v_pk_fma_f32 v[156:157], v[106:107], v[34:35], v[156:157]
	v_pk_fma_f32 v[178:179], v[106:107], v[42:43], v[178:179]
	v_pk_fma_f32 v[180:181], v[106:107], v[38:39], v[180:181]
	v_pk_fma_f32 v[238:239], v[106:107], v[46:47], v[238:239]
	v_add_f32_e32 v147, v156, v157
	v_add_f32_e32 v148, v178, v179
	v_add_f32_e32 v149, v180, v181
	v_add_f32_e32 v150, v238, v239
	v_pk_mul_f32 v[156:157], v[104:105], v[36:37]
	v_pk_mul_f32 v[178:179], v[104:105], v[44:45]
	v_pk_mul_f32 v[180:181], v[104:105], v[40:41]
	v_pk_mul_f32 v[238:239], v[104:105], v[48:49]
	v_pk_fma_f32 v[156:157], v[102:103], v[34:35], v[156:157]
	v_pk_fma_f32 v[178:179], v[102:103], v[42:43], v[178:179]
	v_pk_fma_f32 v[180:181], v[102:103], v[38:39], v[180:181]
	v_pk_fma_f32 v[238:239], v[102:103], v[46:47], v[238:239]
	v_add_f32_e32 v151, v156, v157
	v_add_f32_e32 v152, v178, v179
	v_add_f32_e32 v153, v180, v181
	v_add_f32_e32 v154, v238, v239
	v_mov_b32_dpp v143, v164 quad_perm:[1,2,3,3] row_mask:0xf bank_mask:0xf bound_ctrl:1
	v_add_f32_dpp v240, v164, v164 quad_perm:[1,0,3,2] row_mask:0xf bank_mask:0xf bound_ctrl:1
	v_cndmask_b32_e64 v209, v143, 0, s[28:29]
	v_add_f32_dpp v145, v164, v143 quad_perm:[2,3,3,3] row_mask:0xf bank_mask:0xf bound_ctrl:1
	v_add_f32_dpp v242, v240, v240 quad_perm:[2,3,0,1] row_mask:0xf bank_mask:0xf bound_ctrl:1
	v_add_f32_dpp v136, v136, v136 row_mirror row_mask:0xf bank_mask:0x3 bound_ctrl:1
	v_add_f32_dpp v137, v137, v137 row_mirror row_mask:0xf bank_mask:0x3 bound_ctrl:1
	v_add_f32_dpp v138, v138, v138 row_mirror row_mask:0xf bank_mask:0x3 bound_ctrl:1
	v_add_f32_dpp v139, v139, v139 row_mirror row_mask:0xf bank_mask:0x3 bound_ctrl:1
	v_add_f32_dpp v140, v140, v140 row_mirror row_mask:0xf bank_mask:0x3 bound_ctrl:1
	v_add_f32_dpp v141, v141, v141 row_mirror row_mask:0xf bank_mask:0x3 bound_ctrl:1
	v_add_f32_dpp v142, v142, v142 row_mirror row_mask:0xf bank_mask:0x3 bound_ctrl:1
	v_add_f32_dpp v144, v144, v144 row_mirror row_mask:0xf bank_mask:0x3 bound_ctrl:1
	v_add_f32_dpp v167, v164, v145 quad_perm:[3,3,3,3] row_mask:0xf bank_mask:0xf bound_ctrl:1
	v_add_f32_dpp v136, v147, v147 row_mirror row_mask:0xf bank_mask:0xc bound_ctrl:1
	v_add_f32_dpp v137, v148, v148 row_mirror row_mask:0xf bank_mask:0xc bound_ctrl:1
	v_add_f32_dpp v138, v149, v149 row_mirror row_mask:0xf bank_mask:0xc bound_ctrl:1
	v_add_f32_dpp v139, v150, v150 row_mirror row_mask:0xf bank_mask:0xc bound_ctrl:1
	v_add_f32_dpp v140, v151, v151 row_mirror row_mask:0xf bank_mask:0xc bound_ctrl:1
	v_add_f32_dpp v141, v152, v152 row_mirror row_mask:0xf bank_mask:0xc bound_ctrl:1
	v_add_f32_dpp v142, v153, v153 row_mirror row_mask:0xf bank_mask:0xc bound_ctrl:1
	v_add_f32_dpp v144, v154, v154 row_mirror row_mask:0xf bank_mask:0xc bound_ctrl:1
	v_add_f32_dpp v136, v136, v136 row_half_mirror row_mask:0xf bank_mask:0x5 bound_ctrl:1
	v_add_f32_dpp v137, v137, v137 row_half_mirror row_mask:0xf bank_mask:0x5 bound_ctrl:1
	v_add_f32_dpp v138, v138, v138 row_half_mirror row_mask:0xf bank_mask:0x5 bound_ctrl:1
	v_add_f32_dpp v139, v139, v139 row_half_mirror row_mask:0xf bank_mask:0x5 bound_ctrl:1
	v_add_f32_dpp v136, v140, v140 row_half_mirror row_mask:0xf bank_mask:0xa bound_ctrl:1
	v_add_f32_dpp v137, v141, v141 row_half_mirror row_mask:0xf bank_mask:0xa bound_ctrl:1
	v_add_f32_dpp v138, v142, v142 row_half_mirror row_mask:0xf bank_mask:0xa bound_ctrl:1
	v_add_f32_dpp v139, v144, v144 row_half_mirror row_mask:0xf bank_mask:0xa bound_ctrl:1
	v_add_f32_dpp v136, v136, v136 quad_perm:[2,3,0,1] row_mask:0xf bank_mask:0xf bound_ctrl:1
	v_add_f32_dpp v138, v138, v138 quad_perm:[2,3,0,1] row_mask:0xf bank_mask:0xf bound_ctrl:1
	v_add_f32_dpp v137, v137, v137 quad_perm:[2,3,0,1] row_mask:0xf bank_mask:0xf bound_ctrl:1
	v_add_f32_dpp v139, v139, v139 quad_perm:[2,3,0,1] row_mask:0xf bank_mask:0xf bound_ctrl:1
	v_cndmask_b32_e64 v167, v167, v145, s[28:29]
	v_cndmask_b32_e64 v172, v167, v209, s[24:25]
	v_cndmask_b32_e64 v136, v136, v138, s[24:25]
	v_cndmask_b32_e64 v137, v137, v139, s[24:25]
	v_add_f32_e32 v172, v146, v172
	v_add_f32_e32 v146, v146, v242
	v_add_f32_dpp v136, v136, v136 quad_perm:[1,0,3,2] row_mask:0xf bank_mask:0xf bound_ctrl:1
	v_add_f32_dpp v137, v137, v137 quad_perm:[1,0,3,2] row_mask:0xf bank_mask:0xf bound_ctrl:1
	v_cndmask_b32_e64 v136, v136, v137, s[28:29]
	v_fmac_f32_e32 v136, 0x3fb8aa3b, v172
	s_nop 1
	v_max_f32_dpp v179, v136, v136 quad_perm:[1,0,3,2] row_mask:0xf bank_mask:0xf bound_ctrl:1
	s_nop 1
	v_max_f32_dpp v180, v179, v179 quad_perm:[2,3,0,1] row_mask:0xf bank_mask:0xf bound_ctrl:1
	v_max_f32_e32 v180, v134, v180
	v_sub_f32_e32 v155, v134, v180
	v_sub_f32_e32 v156, v136, v180
	v_mov_b32_e32 v134, v180
	v_exp_f32_e32 v155, v155
	v_exp_f32_e32 v156, v156
	s_nop 0
	v_mov_b32_dpp v137, v155 row_newbcast:0 row_mask:0xf bank_mask:0xf
	v_mov_b32_dpp v142, v155 row_newbcast:4 row_mask:0xf bank_mask:0xf
	v_mov_b32_dpp v150, v155 row_newbcast:8 row_mask:0xf bank_mask:0xf
	v_mov_b32_dpp v178, v155 row_newbcast:12 row_mask:0xf bank_mask:0xf
	v_add_f32_dpp v157, v156, v156 quad_perm:[1,0,3,2] row_mask:0xf bank_mask:0xf bound_ctrl:1
	v_mov_b32_dpp v138, v156 row_newbcast:0 row_mask:0xf bank_mask:0xf
	v_mov_b32_dpp v139, v156 row_newbcast:1 row_mask:0xf bank_mask:0xf
	v_mov_b32_dpp v140, v156 row_newbcast:2 row_mask:0xf bank_mask:0xf
	v_mov_b32_dpp v141, v156 row_newbcast:3 row_mask:0xf bank_mask:0xf
	v_add_f32_dpp v173, v157, v157 quad_perm:[2,3,0,1] row_mask:0xf bank_mask:0xf bound_ctrl:1
	v_mov_b32_dpp v144, v156 row_newbcast:4 row_mask:0xf bank_mask:0xf
	v_mov_b32_dpp v147, v156 row_newbcast:5 row_mask:0xf bank_mask:0xf
	v_mov_b32_dpp v148, v156 row_newbcast:6 row_mask:0xf bank_mask:0xf
	v_mov_b32_dpp v149, v156 row_newbcast:7 row_mask:0xf bank_mask:0xf
	v_fma_f32 v135, v135, v155, v173
	v_mov_b32_dpp v151, v156 row_newbcast:8 row_mask:0xf bank_mask:0xf
	v_mov_b32_dpp v152, v156 row_newbcast:9 row_mask:0xf bank_mask:0xf
	v_mov_b32_dpp v153, v156 row_newbcast:10 row_mask:0xf bank_mask:0xf
	v_mov_b32_dpp v154, v156 row_newbcast:11 row_mask:0xf bank_mask:0xf
	v_mov_b32_dpp v179, v156 row_newbcast:12 row_mask:0xf bank_mask:0xf
	v_mov_b32_dpp v180, v156 row_newbcast:13 row_mask:0xf bank_mask:0xf
	v_mov_b32_dpp v181, v156 row_newbcast:14 row_mask:0xf bank_mask:0xf
	v_mov_b32_dpp v0, v156 row_newbcast:15 row_mask:0xf bank_mask:0xf
	v_pk_mul_f32 v[118:119], v[118:119], v[136:137] op_sel:[0,1] op_sel_hi:[1,1]
	v_pk_mul_f32 v[120:121], v[120:121], v[136:137] op_sel:[0,1] op_sel_hi:[1,1]
	v_pk_mul_f32 v[122:123], v[122:123], v[142:143] op_sel:[0,0] op_sel_hi:[1,0]
	v_pk_mul_f32 v[124:125], v[124:125], v[142:143] op_sel:[0,0] op_sel_hi:[1,0]
	v_pk_mul_f32 v[126:127], v[126:127], v[150:151] op_sel:[0,0] op_sel_hi:[1,0]
	v_pk_mul_f32 v[128:129], v[128:129], v[150:151] op_sel:[0,0] op_sel_hi:[1,0]
	v_pk_mul_f32 v[130:131], v[130:131], v[178:179] op_sel:[0,0] op_sel_hi:[1,0]
	v_pk_mul_f32 v[132:133], v[132:133], v[178:179] op_sel:[0,0] op_sel_hi:[1,0]
	v_pk_fma_f32 v[118:119], v[138:139], v[2:3], v[118:119] op_sel:[0,0,0] op_sel_hi:[0,1,1]
	v_pk_fma_f32 v[120:121], v[138:139], v[4:5], v[120:121] op_sel:[0,0,0] op_sel_hi:[0,1,1]
	v_pk_fma_f32 v[122:123], v[144:145], v[2:3], v[122:123] op_sel:[0,0,0] op_sel_hi:[0,1,1]
	v_pk_fma_f32 v[124:125], v[144:145], v[4:5], v[124:125] op_sel:[0,0,0] op_sel_hi:[0,1,1]
	v_pk_fma_f32 v[126:127], v[150:151], v[2:3], v[126:127] op_sel:[1,0,0] op_sel_hi:[1,1,1]
	v_pk_fma_f32 v[128:129], v[150:151], v[4:5], v[128:129] op_sel:[1,0,0] op_sel_hi:[1,1,1]
	v_pk_fma_f32 v[130:131], v[178:179], v[2:3], v[130:131] op_sel:[1,0,0] op_sel_hi:[1,1,1]
	v_pk_fma_f32 v[132:133], v[178:179], v[4:5], v[132:133] op_sel:[1,0,0] op_sel_hi:[1,1,1]
	v_pk_fma_f32 v[118:119], v[138:139], v[6:7], v[118:119] op_sel:[1,0,0] op_sel_hi:[1,1,1]
	v_pk_fma_f32 v[120:121], v[138:139], v[8:9], v[120:121] op_sel:[1,0,0] op_sel_hi:[1,1,1]
	v_pk_fma_f32 v[122:123], v[146:147], v[6:7], v[122:123] op_sel:[1,0,0] op_sel_hi:[1,1,1]
	v_pk_fma_f32 v[124:125], v[146:147], v[8:9], v[124:125] op_sel:[1,0,0] op_sel_hi:[1,1,1]
	v_pk_fma_f32 v[126:127], v[152:153], v[6:7], v[126:127] op_sel:[0,0,0] op_sel_hi:[0,1,1]
	v_pk_fma_f32 v[128:129], v[152:153], v[8:9], v[128:129] op_sel:[0,0,0] op_sel_hi:[0,1,1]
	v_pk_fma_f32 v[130:131], v[180:181], v[6:7], v[130:131] op_sel:[0,0,0] op_sel_hi:[0,1,1]
	v_pk_fma_f32 v[132:133], v[180:181], v[8:9], v[132:133] op_sel:[0,0,0] op_sel_hi:[0,1,1]
	v_pk_fma_f32 v[118:119], v[140:141], v[10:11], v[118:119] op_sel:[0,0,0] op_sel_hi:[0,1,1]
	v_pk_fma_f32 v[120:121], v[140:141], v[12:13], v[120:121] op_sel:[0,0,0] op_sel_hi:[0,1,1]
	v_pk_fma_f32 v[122:123], v[148:149], v[10:11], v[122:123] op_sel:[0,0,0] op_sel_hi:[0,1,1]
	v_pk_fma_f32 v[124:125], v[148:149], v[12:13], v[124:125] op_sel:[0,0,0] op_sel_hi:[0,1,1]
	v_pk_fma_f32 v[126:127], v[152:153], v[10:11], v[126:127] op_sel:[1,0,0] op_sel_hi:[1,1,1]
	v_pk_fma_f32 v[128:129], v[152:153], v[12:13], v[128:129] op_sel:[1,0,0] op_sel_hi:[1,1,1]
	v_pk_fma_f32 v[130:131], v[180:181], v[10:11], v[130:131] op_sel:[1,0,0] op_sel_hi:[1,1,1]
	v_pk_fma_f32 v[132:133], v[180:181], v[12:13], v[132:133] op_sel:[1,0,0] op_sel_hi:[1,1,1]
	v_pk_fma_f32 v[118:119], v[140:141], v[14:15], v[118:119] op_sel:[1,0,0] op_sel_hi:[1,1,1]
	v_pk_fma_f32 v[120:121], v[140:141], v[16:17], v[120:121] op_sel:[1,0,0] op_sel_hi:[1,1,1]
	v_pk_fma_f32 v[122:123], v[148:149], v[14:15], v[122:123] op_sel:[1,0,0] op_sel_hi:[1,1,1]
	v_pk_fma_f32 v[124:125], v[148:149], v[16:17], v[124:125] op_sel:[1,0,0] op_sel_hi:[1,1,1]
	v_pk_fma_f32 v[126:127], v[154:155], v[14:15], v[126:127] op_sel:[0,0,0] op_sel_hi:[0,1,1]
	v_pk_fma_f32 v[128:129], v[154:155], v[16:17], v[128:129] op_sel:[0,0,0] op_sel_hi:[0,1,1]
	v_pk_fma_f32 v[130:131], v[0:1], v[14:15], v[130:131] op_sel:[0,0,0] op_sel_hi:[0,1,1]
	v_pk_fma_f32 v[132:133], v[0:1], v[16:17], v[132:133] op_sel:[0,0,0] op_sel_hi:[0,1,1]
	s_waitcnt vmcnt(9)
	v_pk_mul_f32 v[156:157], v[116:117], v[84:85]
	v_pk_mul_f32 v[178:179], v[116:117], v[88:89]
	v_pk_mul_f32 v[180:181], v[116:117], v[92:93]
	v_pk_mul_f32 v[238:239], v[116:117], v[96:97]
	v_pk_fma_f32 v[156:157], v[114:115], v[82:83], v[156:157]
	v_pk_fma_f32 v[178:179], v[114:115], v[86:87], v[178:179]
	v_pk_fma_f32 v[180:181], v[114:115], v[90:91], v[180:181]
	v_pk_fma_f32 v[238:239], v[114:115], v[94:95], v[238:239]
	v_add_f32_e32 v136, v156, v157
	v_add_f32_e32 v137, v178, v179
	v_add_f32_e32 v138, v180, v181
	v_add_f32_e32 v139, v238, v239
	v_pk_mul_f32 v[156:157], v[112:113], v[84:85]
	v_pk_mul_f32 v[178:179], v[112:113], v[88:89]
	v_pk_mul_f32 v[180:181], v[112:113], v[92:93]
	v_pk_mul_f32 v[238:239], v[112:113], v[96:97]
	v_pk_fma_f32 v[156:157], v[110:111], v[82:83], v[156:157]
	v_pk_fma_f32 v[178:179], v[110:111], v[86:87], v[178:179]
	v_pk_fma_f32 v[180:181], v[110:111], v[90:91], v[180:181]
	v_pk_fma_f32 v[238:239], v[110:111], v[94:95], v[238:239]
	v_add_f32_e32 v140, v156, v157
	v_add_f32_e32 v141, v178, v179
	v_add_f32_e32 v142, v180, v181
	v_add_f32_e32 v144, v238, v239
	v_pk_mul_f32 v[156:157], v[108:109], v[84:85]
	v_pk_mul_f32 v[178:179], v[108:109], v[88:89]
	v_pk_mul_f32 v[180:181], v[108:109], v[92:93]
	v_pk_mul_f32 v[238:239], v[108:109], v[96:97]
	v_pk_fma_f32 v[156:157], v[106:107], v[82:83], v[156:157]
	v_pk_fma_f32 v[178:179], v[106:107], v[86:87], v[178:179]
	v_pk_fma_f32 v[180:181], v[106:107], v[90:91], v[180:181]
	v_pk_fma_f32 v[238:239], v[106:107], v[94:95], v[238:239]
	v_add_f32_e32 v147, v156, v157
	v_add_f32_e32 v148, v178, v179
	v_add_f32_e32 v149, v180, v181
	v_add_f32_e32 v150, v238, v239
	v_pk_mul_f32 v[156:157], v[104:105], v[84:85]
	v_pk_mul_f32 v[178:179], v[104:105], v[88:89]
	v_pk_mul_f32 v[180:181], v[104:105], v[92:93]
	v_pk_mul_f32 v[238:239], v[104:105], v[96:97]
	v_pk_fma_f32 v[156:157], v[102:103], v[82:83], v[156:157]
	v_pk_fma_f32 v[178:179], v[102:103], v[86:87], v[178:179]
	v_pk_fma_f32 v[180:181], v[102:103], v[90:91], v[180:181]
	v_pk_fma_f32 v[238:239], v[102:103], v[94:95], v[238:239]
	v_add_f32_e32 v151, v156, v157
	v_add_f32_e32 v152, v178, v179
	v_add_f32_e32 v153, v180, v181
	v_add_f32_e32 v154, v238, v239
	v_mov_b32_dpp v143, v165 quad_perm:[1,2,3,3] row_mask:0xf bank_mask:0xf bound_ctrl:1
	v_add_f32_dpp v240, v165, v165 quad_perm:[1,0,3,2] row_mask:0xf bank_mask:0xf bound_ctrl:1
	v_cndmask_b32_e64 v209, v143, 0, s[28:29]
	v_add_f32_dpp v145, v165, v143 quad_perm:[2,3,3,3] row_mask:0xf bank_mask:0xf bound_ctrl:1
	v_add_f32_dpp v242, v240, v240 quad_perm:[2,3,0,1] row_mask:0xf bank_mask:0xf bound_ctrl:1
	v_add_f32_dpp v136, v136, v136 row_mirror row_mask:0xf bank_mask:0x3 bound_ctrl:1
	v_add_f32_dpp v137, v137, v137 row_mirror row_mask:0xf bank_mask:0x3 bound_ctrl:1
	v_add_f32_dpp v138, v138, v138 row_mirror row_mask:0xf bank_mask:0x3 bound_ctrl:1
	v_add_f32_dpp v139, v139, v139 row_mirror row_mask:0xf bank_mask:0x3 bound_ctrl:1
	v_add_f32_dpp v140, v140, v140 row_mirror row_mask:0xf bank_mask:0x3 bound_ctrl:1
	v_add_f32_dpp v141, v141, v141 row_mirror row_mask:0xf bank_mask:0x3 bound_ctrl:1
	v_add_f32_dpp v142, v142, v142 row_mirror row_mask:0xf bank_mask:0x3 bound_ctrl:1
	v_add_f32_dpp v144, v144, v144 row_mirror row_mask:0xf bank_mask:0x3 bound_ctrl:1
	v_add_f32_dpp v167, v165, v145 quad_perm:[3,3,3,3] row_mask:0xf bank_mask:0xf bound_ctrl:1
	v_add_f32_dpp v136, v147, v147 row_mirror row_mask:0xf bank_mask:0xc bound_ctrl:1
	v_add_f32_dpp v137, v148, v148 row_mirror row_mask:0xf bank_mask:0xc bound_ctrl:1
	v_add_f32_dpp v138, v149, v149 row_mirror row_mask:0xf bank_mask:0xc bound_ctrl:1
	v_add_f32_dpp v139, v150, v150 row_mirror row_mask:0xf bank_mask:0xc bound_ctrl:1
	v_add_f32_dpp v140, v151, v151 row_mirror row_mask:0xf bank_mask:0xc bound_ctrl:1
	v_add_f32_dpp v141, v152, v152 row_mirror row_mask:0xf bank_mask:0xc bound_ctrl:1
	v_add_f32_dpp v142, v153, v153 row_mirror row_mask:0xf bank_mask:0xc bound_ctrl:1
	v_add_f32_dpp v144, v154, v154 row_mirror row_mask:0xf bank_mask:0xc bound_ctrl:1
	v_add_f32_dpp v136, v136, v136 row_half_mirror row_mask:0xf bank_mask:0x5 bound_ctrl:1
	v_add_f32_dpp v137, v137, v137 row_half_mirror row_mask:0xf bank_mask:0x5 bound_ctrl:1
	v_add_f32_dpp v138, v138, v138 row_half_mirror row_mask:0xf bank_mask:0x5 bound_ctrl:1
	v_add_f32_dpp v139, v139, v139 row_half_mirror row_mask:0xf bank_mask:0x5 bound_ctrl:1
	v_add_f32_dpp v136, v140, v140 row_half_mirror row_mask:0xf bank_mask:0xa bound_ctrl:1
	v_add_f32_dpp v137, v141, v141 row_half_mirror row_mask:0xf bank_mask:0xa bound_ctrl:1
	v_add_f32_dpp v138, v142, v142 row_half_mirror row_mask:0xf bank_mask:0xa bound_ctrl:1
	v_add_f32_dpp v139, v144, v144 row_half_mirror row_mask:0xf bank_mask:0xa bound_ctrl:1
	v_add_f32_dpp v136, v136, v136 quad_perm:[2,3,0,1] row_mask:0xf bank_mask:0xf bound_ctrl:1
	v_add_f32_dpp v138, v138, v138 quad_perm:[2,3,0,1] row_mask:0xf bank_mask:0xf bound_ctrl:1
	v_add_f32_dpp v137, v137, v137 quad_perm:[2,3,0,1] row_mask:0xf bank_mask:0xf bound_ctrl:1
	v_add_f32_dpp v139, v139, v139 quad_perm:[2,3,0,1] row_mask:0xf bank_mask:0xf bound_ctrl:1
	v_cndmask_b32_e64 v167, v167, v145, s[28:29]
	v_cndmask_b32_e64 v172, v167, v209, s[24:25]
	v_cndmask_b32_e64 v136, v136, v138, s[24:25]
	v_cndmask_b32_e64 v137, v137, v139, s[24:25]
	v_add_f32_e32 v172, v146, v172
	v_add_f32_e32 v146, v146, v242
	v_add_f32_dpp v136, v136, v136 quad_perm:[1,0,3,2] row_mask:0xf bank_mask:0xf bound_ctrl:1
	v_add_f32_dpp v137, v137, v137 quad_perm:[1,0,3,2] row_mask:0xf bank_mask:0xf bound_ctrl:1
	v_cndmask_b32_e64 v136, v136, v137, s[28:29]
	v_fmac_f32_e32 v136, 0x3fb8aa3b, v172
	s_nop 1
	v_max_f32_dpp v179, v136, v136 quad_perm:[1,0,3,2] row_mask:0xf bank_mask:0xf bound_ctrl:1
	s_nop 1
	v_max_f32_dpp v180, v179, v179 quad_perm:[2,3,0,1] row_mask:0xf bank_mask:0xf bound_ctrl:1
	v_max_f32_e32 v180, v134, v180
	v_sub_f32_e32 v155, v134, v180
	v_sub_f32_e32 v156, v136, v180
	v_mov_b32_e32 v134, v180
	v_exp_f32_e32 v155, v155
	v_exp_f32_e32 v156, v156
	s_nop 0
	v_mov_b32_dpp v137, v155 row_newbcast:0 row_mask:0xf bank_mask:0xf
	v_mov_b32_dpp v142, v155 row_newbcast:4 row_mask:0xf bank_mask:0xf
	v_mov_b32_dpp v150, v155 row_newbcast:8 row_mask:0xf bank_mask:0xf
	v_mov_b32_dpp v178, v155 row_newbcast:12 row_mask:0xf bank_mask:0xf
	v_add_f32_dpp v157, v156, v156 quad_perm:[1,0,3,2] row_mask:0xf bank_mask:0xf bound_ctrl:1
	v_mov_b32_dpp v138, v156 row_newbcast:0 row_mask:0xf bank_mask:0xf
	v_mov_b32_dpp v139, v156 row_newbcast:1 row_mask:0xf bank_mask:0xf
	v_mov_b32_dpp v140, v156 row_newbcast:2 row_mask:0xf bank_mask:0xf
	v_mov_b32_dpp v141, v156 row_newbcast:3 row_mask:0xf bank_mask:0xf
	v_add_f32_dpp v173, v157, v157 quad_perm:[2,3,0,1] row_mask:0xf bank_mask:0xf bound_ctrl:1
	v_mov_b32_dpp v144, v156 row_newbcast:4 row_mask:0xf bank_mask:0xf
	v_mov_b32_dpp v147, v156 row_newbcast:5 row_mask:0xf bank_mask:0xf
	v_mov_b32_dpp v148, v156 row_newbcast:6 row_mask:0xf bank_mask:0xf
	v_mov_b32_dpp v149, v156 row_newbcast:7 row_mask:0xf bank_mask:0xf
	v_fma_f32 v135, v135, v155, v173
	v_mov_b32_dpp v151, v156 row_newbcast:8 row_mask:0xf bank_mask:0xf
	v_mov_b32_dpp v152, v156 row_newbcast:9 row_mask:0xf bank_mask:0xf
	v_mov_b32_dpp v153, v156 row_newbcast:10 row_mask:0xf bank_mask:0xf
	v_mov_b32_dpp v154, v156 row_newbcast:11 row_mask:0xf bank_mask:0xf
	v_mov_b32_dpp v179, v156 row_newbcast:12 row_mask:0xf bank_mask:0xf
	v_mov_b32_dpp v180, v156 row_newbcast:13 row_mask:0xf bank_mask:0xf
	v_mov_b32_dpp v181, v156 row_newbcast:14 row_mask:0xf bank_mask:0xf
	v_mov_b32_dpp v0, v156 row_newbcast:15 row_mask:0xf bank_mask:0xf
	v_pk_mul_f32 v[118:119], v[118:119], v[136:137] op_sel:[0,1] op_sel_hi:[1,1]
	v_pk_mul_f32 v[120:121], v[120:121], v[136:137] op_sel:[0,1] op_sel_hi:[1,1]
	v_pk_mul_f32 v[122:123], v[122:123], v[142:143] op_sel:[0,0] op_sel_hi:[1,0]
	v_pk_mul_f32 v[124:125], v[124:125], v[142:143] op_sel:[0,0] op_sel_hi:[1,0]
	v_pk_mul_f32 v[126:127], v[126:127], v[150:151] op_sel:[0,0] op_sel_hi:[1,0]
	v_pk_mul_f32 v[128:129], v[128:129], v[150:151] op_sel:[0,0] op_sel_hi:[1,0]
	v_pk_mul_f32 v[130:131], v[130:131], v[178:179] op_sel:[0,0] op_sel_hi:[1,0]
	v_pk_mul_f32 v[132:133], v[132:133], v[178:179] op_sel:[0,0] op_sel_hi:[1,0]
	v_pk_fma_f32 v[118:119], v[138:139], v[66:67], v[118:119] op_sel:[0,0,0] op_sel_hi:[0,1,1]
	v_pk_fma_f32 v[120:121], v[138:139], v[68:69], v[120:121] op_sel:[0,0,0] op_sel_hi:[0,1,1]
	v_pk_fma_f32 v[122:123], v[144:145], v[66:67], v[122:123] op_sel:[0,0,0] op_sel_hi:[0,1,1]
	v_pk_fma_f32 v[124:125], v[144:145], v[68:69], v[124:125] op_sel:[0,0,0] op_sel_hi:[0,1,1]
	v_pk_fma_f32 v[126:127], v[150:151], v[66:67], v[126:127] op_sel:[1,0,0] op_sel_hi:[1,1,1]
	v_pk_fma_f32 v[128:129], v[150:151], v[68:69], v[128:129] op_sel:[1,0,0] op_sel_hi:[1,1,1]
	v_pk_fma_f32 v[130:131], v[178:179], v[66:67], v[130:131] op_sel:[1,0,0] op_sel_hi:[1,1,1]
	v_pk_fma_f32 v[132:133], v[178:179], v[68:69], v[132:133] op_sel:[1,0,0] op_sel_hi:[1,1,1]
	v_pk_fma_f32 v[118:119], v[138:139], v[70:71], v[118:119] op_sel:[1,0,0] op_sel_hi:[1,1,1]
	v_pk_fma_f32 v[120:121], v[138:139], v[72:73], v[120:121] op_sel:[1,0,0] op_sel_hi:[1,1,1]
	v_pk_fma_f32 v[122:123], v[146:147], v[70:71], v[122:123] op_sel:[1,0,0] op_sel_hi:[1,1,1]
	v_pk_fma_f32 v[124:125], v[146:147], v[72:73], v[124:125] op_sel:[1,0,0] op_sel_hi:[1,1,1]
	v_pk_fma_f32 v[126:127], v[152:153], v[70:71], v[126:127] op_sel:[0,0,0] op_sel_hi:[0,1,1]
	v_pk_fma_f32 v[128:129], v[152:153], v[72:73], v[128:129] op_sel:[0,0,0] op_sel_hi:[0,1,1]
	v_pk_fma_f32 v[130:131], v[180:181], v[70:71], v[130:131] op_sel:[0,0,0] op_sel_hi:[0,1,1]
	v_pk_fma_f32 v[132:133], v[180:181], v[72:73], v[132:133] op_sel:[0,0,0] op_sel_hi:[0,1,1]
	v_pk_fma_f32 v[118:119], v[140:141], v[74:75], v[118:119] op_sel:[0,0,0] op_sel_hi:[0,1,1]
	v_pk_fma_f32 v[120:121], v[140:141], v[76:77], v[120:121] op_sel:[0,0,0] op_sel_hi:[0,1,1]
	v_pk_fma_f32 v[122:123], v[148:149], v[74:75], v[122:123] op_sel:[0,0,0] op_sel_hi:[0,1,1]
	v_pk_fma_f32 v[124:125], v[148:149], v[76:77], v[124:125] op_sel:[0,0,0] op_sel_hi:[0,1,1]
	v_pk_fma_f32 v[126:127], v[152:153], v[74:75], v[126:127] op_sel:[1,0,0] op_sel_hi:[1,1,1]
	v_pk_fma_f32 v[128:129], v[152:153], v[76:77], v[128:129] op_sel:[1,0,0] op_sel_hi:[1,1,1]
	v_pk_fma_f32 v[130:131], v[180:181], v[74:75], v[130:131] op_sel:[1,0,0] op_sel_hi:[1,1,1]
	v_pk_fma_f32 v[132:133], v[180:181], v[76:77], v[132:133] op_sel:[1,0,0] op_sel_hi:[1,1,1]
	v_pk_fma_f32 v[118:119], v[140:141], v[78:79], v[118:119] op_sel:[1,0,0] op_sel_hi:[1,1,1]
	v_pk_fma_f32 v[120:121], v[140:141], v[80:81], v[120:121] op_sel:[1,0,0] op_sel_hi:[1,1,1]
	v_pk_fma_f32 v[122:123], v[148:149], v[78:79], v[122:123] op_sel:[1,0,0] op_sel_hi:[1,1,1]
	v_pk_fma_f32 v[124:125], v[148:149], v[80:81], v[124:125] op_sel:[1,0,0] op_sel_hi:[1,1,1]
	v_pk_fma_f32 v[126:127], v[154:155], v[78:79], v[126:127] op_sel:[0,0,0] op_sel_hi:[0,1,1]
	v_pk_fma_f32 v[128:129], v[154:155], v[80:81], v[128:129] op_sel:[0,0,0] op_sel_hi:[0,1,1]
	v_pk_fma_f32 v[130:131], v[0:1], v[78:79], v[130:131] op_sel:[0,0,0] op_sel_hi:[0,1,1]
	v_pk_fma_f32 v[132:133], v[0:1], v[80:81], v[132:133] op_sel:[0,0,0] op_sel_hi:[0,1,1]
	s_waitcnt vmcnt(0)
	v_pk_mul_f32 v[156:157], v[116:117], v[212:213]
	v_pk_mul_f32 v[178:179], v[116:117], v[228:229]
	v_pk_mul_f32 v[180:181], v[116:117], v[232:233]
	v_pk_mul_f32 v[238:239], v[116:117], v[236:237]
	v_pk_fma_f32 v[156:157], v[114:115], v[210:211], v[156:157]
	v_pk_fma_f32 v[178:179], v[114:115], v[226:227], v[178:179]
	v_pk_fma_f32 v[180:181], v[114:115], v[230:231], v[180:181]
	v_pk_fma_f32 v[238:239], v[114:115], v[234:235], v[238:239]
	v_add_f32_e32 v136, v156, v157
	v_add_f32_e32 v137, v178, v179
	v_add_f32_e32 v138, v180, v181
	v_add_f32_e32 v139, v238, v239
	v_pk_mul_f32 v[156:157], v[112:113], v[212:213]
	v_pk_mul_f32 v[178:179], v[112:113], v[228:229]
	v_pk_mul_f32 v[180:181], v[112:113], v[232:233]
	v_pk_mul_f32 v[238:239], v[112:113], v[236:237]
	v_pk_fma_f32 v[156:157], v[110:111], v[210:211], v[156:157]
	v_pk_fma_f32 v[178:179], v[110:111], v[226:227], v[178:179]
	v_pk_fma_f32 v[180:181], v[110:111], v[230:231], v[180:181]
	v_pk_fma_f32 v[238:239], v[110:111], v[234:235], v[238:239]
	v_add_f32_e32 v140, v156, v157
	v_add_f32_e32 v141, v178, v179
	v_add_f32_e32 v142, v180, v181
	v_add_f32_e32 v144, v238, v239
	v_pk_mul_f32 v[156:157], v[108:109], v[212:213]
	v_pk_mul_f32 v[178:179], v[108:109], v[228:229]
	v_pk_mul_f32 v[180:181], v[108:109], v[232:233]
	v_pk_mul_f32 v[238:239], v[108:109], v[236:237]
	v_pk_fma_f32 v[156:157], v[106:107], v[210:211], v[156:157]
	v_pk_fma_f32 v[178:179], v[106:107], v[226:227], v[178:179]
	v_pk_fma_f32 v[180:181], v[106:107], v[230:231], v[180:181]
	v_pk_fma_f32 v[238:239], v[106:107], v[234:235], v[238:239]
	v_add_f32_e32 v147, v156, v157
	v_add_f32_e32 v148, v178, v179
	v_add_f32_e32 v149, v180, v181
	v_add_f32_e32 v150, v238, v239
	v_pk_mul_f32 v[156:157], v[104:105], v[212:213]
	v_pk_mul_f32 v[178:179], v[104:105], v[228:229]
	v_pk_mul_f32 v[180:181], v[104:105], v[232:233]
	v_pk_mul_f32 v[238:239], v[104:105], v[236:237]
	v_pk_fma_f32 v[156:157], v[102:103], v[210:211], v[156:157]
	v_pk_fma_f32 v[178:179], v[102:103], v[226:227], v[178:179]
	v_pk_fma_f32 v[180:181], v[102:103], v[230:231], v[180:181]
	v_pk_fma_f32 v[238:239], v[102:103], v[234:235], v[238:239]
	v_add_f32_e32 v151, v156, v157
	v_add_f32_e32 v152, v178, v179
	v_add_f32_e32 v153, v180, v181
	v_add_f32_e32 v154, v238, v239
	v_mov_b32_dpp v143, v166 quad_perm:[1,2,3,3] row_mask:0xf bank_mask:0xf bound_ctrl:1
	v_add_f32_dpp v240, v166, v166 quad_perm:[1,0,3,2] row_mask:0xf bank_mask:0xf bound_ctrl:1
	v_cndmask_b32_e64 v209, v143, 0, s[28:29]
	v_add_f32_dpp v145, v166, v143 quad_perm:[2,3,3,3] row_mask:0xf bank_mask:0xf bound_ctrl:1
	v_add_f32_dpp v242, v240, v240 quad_perm:[2,3,0,1] row_mask:0xf bank_mask:0xf bound_ctrl:1
	v_add_f32_dpp v136, v136, v136 row_mirror row_mask:0xf bank_mask:0x3 bound_ctrl:1
	v_add_f32_dpp v137, v137, v137 row_mirror row_mask:0xf bank_mask:0x3 bound_ctrl:1
	v_add_f32_dpp v138, v138, v138 row_mirror row_mask:0xf bank_mask:0x3 bound_ctrl:1
	v_add_f32_dpp v139, v139, v139 row_mirror row_mask:0xf bank_mask:0x3 bound_ctrl:1
	v_add_f32_dpp v140, v140, v140 row_mirror row_mask:0xf bank_mask:0x3 bound_ctrl:1
	v_add_f32_dpp v141, v141, v141 row_mirror row_mask:0xf bank_mask:0x3 bound_ctrl:1
	v_add_f32_dpp v142, v142, v142 row_mirror row_mask:0xf bank_mask:0x3 bound_ctrl:1
	v_add_f32_dpp v144, v144, v144 row_mirror row_mask:0xf bank_mask:0x3 bound_ctrl:1
	v_add_f32_dpp v167, v166, v145 quad_perm:[3,3,3,3] row_mask:0xf bank_mask:0xf bound_ctrl:1
	v_add_f32_dpp v136, v147, v147 row_mirror row_mask:0xf bank_mask:0xc bound_ctrl:1
	v_add_f32_dpp v137, v148, v148 row_mirror row_mask:0xf bank_mask:0xc bound_ctrl:1
	v_add_f32_dpp v138, v149, v149 row_mirror row_mask:0xf bank_mask:0xc bound_ctrl:1
	v_add_f32_dpp v139, v150, v150 row_mirror row_mask:0xf bank_mask:0xc bound_ctrl:1
	v_add_f32_dpp v140, v151, v151 row_mirror row_mask:0xf bank_mask:0xc bound_ctrl:1
	v_add_f32_dpp v141, v152, v152 row_mirror row_mask:0xf bank_mask:0xc bound_ctrl:1
	v_add_f32_dpp v142, v153, v153 row_mirror row_mask:0xf bank_mask:0xc bound_ctrl:1
	v_add_f32_dpp v144, v154, v154 row_mirror row_mask:0xf bank_mask:0xc bound_ctrl:1
	v_add_f32_dpp v136, v136, v136 row_half_mirror row_mask:0xf bank_mask:0x5 bound_ctrl:1
	v_add_f32_dpp v137, v137, v137 row_half_mirror row_mask:0xf bank_mask:0x5 bound_ctrl:1
	v_add_f32_dpp v138, v138, v138 row_half_mirror row_mask:0xf bank_mask:0x5 bound_ctrl:1
	v_add_f32_dpp v139, v139, v139 row_half_mirror row_mask:0xf bank_mask:0x5 bound_ctrl:1
	v_add_f32_dpp v136, v140, v140 row_half_mirror row_mask:0xf bank_mask:0xa bound_ctrl:1
	v_add_f32_dpp v137, v141, v141 row_half_mirror row_mask:0xf bank_mask:0xa bound_ctrl:1
	v_add_f32_dpp v138, v142, v142 row_half_mirror row_mask:0xf bank_mask:0xa bound_ctrl:1
	v_add_f32_dpp v139, v144, v144 row_half_mirror row_mask:0xf bank_mask:0xa bound_ctrl:1
	v_add_f32_dpp v136, v136, v136 quad_perm:[2,3,0,1] row_mask:0xf bank_mask:0xf bound_ctrl:1
	v_add_f32_dpp v138, v138, v138 quad_perm:[2,3,0,1] row_mask:0xf bank_mask:0xf bound_ctrl:1
	v_add_f32_dpp v137, v137, v137 quad_perm:[2,3,0,1] row_mask:0xf bank_mask:0xf bound_ctrl:1
	v_add_f32_dpp v139, v139, v139 quad_perm:[2,3,0,1] row_mask:0xf bank_mask:0xf bound_ctrl:1
	v_cndmask_b32_e64 v167, v167, v145, s[28:29]
	v_cndmask_b32_e64 v172, v167, v209, s[24:25]
	v_cndmask_b32_e64 v136, v136, v138, s[24:25]
	v_cndmask_b32_e64 v137, v137, v139, s[24:25]
	v_add_f32_e32 v172, v146, v172
	v_add_f32_e32 v146, v146, v242
	v_add_f32_dpp v136, v136, v136 quad_perm:[1,0,3,2] row_mask:0xf bank_mask:0xf bound_ctrl:1
	v_add_f32_dpp v137, v137, v137 quad_perm:[1,0,3,2] row_mask:0xf bank_mask:0xf bound_ctrl:1
	v_cndmask_b32_e64 v136, v136, v137, s[28:29]
	v_fmac_f32_e32 v136, 0x3fb8aa3b, v172
	s_nop 1
	v_max_f32_dpp v179, v136, v136 quad_perm:[1,0,3,2] row_mask:0xf bank_mask:0xf bound_ctrl:1
	s_nop 1
	v_max_f32_dpp v180, v179, v179 quad_perm:[2,3,0,1] row_mask:0xf bank_mask:0xf bound_ctrl:1
	v_max_f32_e32 v180, v134, v180
	v_sub_f32_e32 v155, v134, v180
	v_sub_f32_e32 v156, v136, v180
	v_mov_b32_e32 v134, v180
	v_exp_f32_e32 v155, v155
	v_exp_f32_e32 v156, v156
	s_nop 0
	v_mov_b32_dpp v137, v155 row_newbcast:0 row_mask:0xf bank_mask:0xf
	v_mov_b32_dpp v142, v155 row_newbcast:4 row_mask:0xf bank_mask:0xf
	v_mov_b32_dpp v150, v155 row_newbcast:8 row_mask:0xf bank_mask:0xf
	v_mov_b32_dpp v178, v155 row_newbcast:12 row_mask:0xf bank_mask:0xf
	v_add_f32_dpp v157, v156, v156 quad_perm:[1,0,3,2] row_mask:0xf bank_mask:0xf bound_ctrl:1
	v_mov_b32_dpp v138, v156 row_newbcast:0 row_mask:0xf bank_mask:0xf
	v_mov_b32_dpp v139, v156 row_newbcast:1 row_mask:0xf bank_mask:0xf
	v_mov_b32_dpp v140, v156 row_newbcast:2 row_mask:0xf bank_mask:0xf
	v_mov_b32_dpp v141, v156 row_newbcast:3 row_mask:0xf bank_mask:0xf
	v_add_f32_dpp v173, v157, v157 quad_perm:[2,3,0,1] row_mask:0xf bank_mask:0xf bound_ctrl:1
	v_mov_b32_dpp v144, v156 row_newbcast:4 row_mask:0xf bank_mask:0xf
	v_mov_b32_dpp v147, v156 row_newbcast:5 row_mask:0xf bank_mask:0xf
	v_mov_b32_dpp v148, v156 row_newbcast:6 row_mask:0xf bank_mask:0xf
	v_mov_b32_dpp v149, v156 row_newbcast:7 row_mask:0xf bank_mask:0xf
	v_fma_f32 v135, v135, v155, v173
	v_mov_b32_dpp v151, v156 row_newbcast:8 row_mask:0xf bank_mask:0xf
	v_mov_b32_dpp v152, v156 row_newbcast:9 row_mask:0xf bank_mask:0xf
	v_mov_b32_dpp v153, v156 row_newbcast:10 row_mask:0xf bank_mask:0xf
	v_mov_b32_dpp v154, v156 row_newbcast:11 row_mask:0xf bank_mask:0xf
	v_mov_b32_dpp v179, v156 row_newbcast:12 row_mask:0xf bank_mask:0xf
	v_mov_b32_dpp v180, v156 row_newbcast:13 row_mask:0xf bank_mask:0xf
	v_mov_b32_dpp v181, v156 row_newbcast:14 row_mask:0xf bank_mask:0xf
	v_mov_b32_dpp v0, v156 row_newbcast:15 row_mask:0xf bank_mask:0xf
	v_pk_mul_f32 v[118:119], v[118:119], v[136:137] op_sel:[0,1] op_sel_hi:[1,1]
	v_pk_mul_f32 v[120:121], v[120:121], v[136:137] op_sel:[0,1] op_sel_hi:[1,1]
	v_pk_mul_f32 v[122:123], v[122:123], v[142:143] op_sel:[0,0] op_sel_hi:[1,0]
	v_pk_mul_f32 v[124:125], v[124:125], v[142:143] op_sel:[0,0] op_sel_hi:[1,0]
	v_pk_mul_f32 v[126:127], v[126:127], v[150:151] op_sel:[0,0] op_sel_hi:[1,0]
	v_pk_mul_f32 v[128:129], v[128:129], v[150:151] op_sel:[0,0] op_sel_hi:[1,0]
	v_pk_mul_f32 v[130:131], v[130:131], v[178:179] op_sel:[0,0] op_sel_hi:[1,0]
	v_pk_mul_f32 v[132:133], v[132:133], v[178:179] op_sel:[0,0] op_sel_hi:[1,0]
	v_pk_fma_f32 v[118:119], v[138:139], v[250:251], v[118:119] op_sel:[0,0,0] op_sel_hi:[0,1,1]
	v_pk_fma_f32 v[120:121], v[138:139], v[252:253], v[120:121] op_sel:[0,0,0] op_sel_hi:[0,1,1]
	v_pk_fma_f32 v[122:123], v[144:145], v[250:251], v[122:123] op_sel:[0,0,0] op_sel_hi:[0,1,1]
	v_pk_fma_f32 v[124:125], v[144:145], v[252:253], v[124:125] op_sel:[0,0,0] op_sel_hi:[0,1,1]
	v_pk_fma_f32 v[126:127], v[150:151], v[250:251], v[126:127] op_sel:[1,0,0] op_sel_hi:[1,1,1]
	v_pk_fma_f32 v[128:129], v[150:151], v[252:253], v[128:129] op_sel:[1,0,0] op_sel_hi:[1,1,1]
	v_pk_fma_f32 v[130:131], v[178:179], v[250:251], v[130:131] op_sel:[1,0,0] op_sel_hi:[1,1,1]
	v_pk_fma_f32 v[132:133], v[178:179], v[252:253], v[132:133] op_sel:[1,0,0] op_sel_hi:[1,1,1]
	v_pk_fma_f32 v[118:119], v[138:139], v[98:99], v[118:119] op_sel:[1,0,0] op_sel_hi:[1,1,1]
	v_pk_fma_f32 v[120:121], v[138:139], v[100:101], v[120:121] op_sel:[1,0,0] op_sel_hi:[1,1,1]
	v_pk_fma_f32 v[122:123], v[146:147], v[98:99], v[122:123] op_sel:[1,0,0] op_sel_hi:[1,1,1]
	v_pk_fma_f32 v[124:125], v[146:147], v[100:101], v[124:125] op_sel:[1,0,0] op_sel_hi:[1,1,1]
	v_pk_fma_f32 v[126:127], v[152:153], v[98:99], v[126:127] op_sel:[0,0,0] op_sel_hi:[0,1,1]
	v_pk_fma_f32 v[128:129], v[152:153], v[100:101], v[128:129] op_sel:[0,0,0] op_sel_hi:[0,1,1]
	v_pk_fma_f32 v[130:131], v[180:181], v[98:99], v[130:131] op_sel:[0,0,0] op_sel_hi:[0,1,1]
	v_pk_fma_f32 v[132:133], v[180:181], v[100:101], v[132:133] op_sel:[0,0,0] op_sel_hi:[0,1,1]
	v_pk_fma_f32 v[118:119], v[140:141], v[174:175], v[118:119] op_sel:[0,0,0] op_sel_hi:[0,1,1]
	v_pk_fma_f32 v[120:121], v[140:141], v[176:177], v[120:121] op_sel:[0,0,0] op_sel_hi:[0,1,1]
	v_pk_fma_f32 v[122:123], v[148:149], v[174:175], v[122:123] op_sel:[0,0,0] op_sel_hi:[0,1,1]
	v_pk_fma_f32 v[124:125], v[148:149], v[176:177], v[124:125] op_sel:[0,0,0] op_sel_hi:[0,1,1]
	v_pk_fma_f32 v[126:127], v[152:153], v[174:175], v[126:127] op_sel:[1,0,0] op_sel_hi:[1,1,1]
	v_pk_fma_f32 v[128:129], v[152:153], v[176:177], v[128:129] op_sel:[1,0,0] op_sel_hi:[1,1,1]
	v_pk_fma_f32 v[130:131], v[180:181], v[174:175], v[130:131] op_sel:[1,0,0] op_sel_hi:[1,1,1]
	v_pk_fma_f32 v[132:133], v[180:181], v[176:177], v[132:133] op_sel:[1,0,0] op_sel_hi:[1,1,1]
	v_pk_fma_f32 v[118:119], v[140:141], v[168:169], v[118:119] op_sel:[1,0,0] op_sel_hi:[1,1,1]
	v_pk_fma_f32 v[120:121], v[140:141], v[170:171], v[120:121] op_sel:[1,0,0] op_sel_hi:[1,1,1]
	v_pk_fma_f32 v[122:123], v[148:149], v[168:169], v[122:123] op_sel:[1,0,0] op_sel_hi:[1,1,1]
	v_pk_fma_f32 v[124:125], v[148:149], v[170:171], v[124:125] op_sel:[1,0,0] op_sel_hi:[1,1,1]
	v_pk_fma_f32 v[126:127], v[154:155], v[168:169], v[126:127] op_sel:[0,0,0] op_sel_hi:[0,1,1]
	v_pk_fma_f32 v[128:129], v[154:155], v[170:171], v[128:129] op_sel:[0,0,0] op_sel_hi:[0,1,1]
	v_pk_fma_f32 v[130:131], v[0:1], v[168:169], v[130:131] op_sel:[0,0,0] op_sel_hi:[0,1,1]
	v_pk_fma_f32 v[132:133], v[0:1], v[170:171], v[132:133] op_sel:[0,0,0] op_sel_hi:[0,1,1]
	s_load_dwordx2 s[0:1], s[42:43], 0x100
	v_lshl_add_u32 v155, s40, 2, v160
	v_lshlrev_b32_e32 v156, 10, v155
	v_lshl_add_u32 v156, v159, 4, v156
	v_lshlrev_b32_e32 v157, 5, v155
	v_lshrrev_b32_e32 v173, 2, v159
	v_lshl_add_u32 v157, v173, 3, v157
	v_and_b32_e32 v173, 3, v159
	v_cmp_eq_u32_e32 vcc, 0, v173
	s_waitcnt lgkmcnt(0)
	s_add_u32 s4, s0, 0x4780000
	s_addc_u32 s5, s1, 0
	s_add_u32 s6, s0, 0x4f80000
	s_addc_u32 s7, s1, 0
	global_store_dwordx4 v156, v[118:121], s[4:5]
	global_store_dwordx4 v156, v[122:125], s[4:5] offset:256
	global_store_dwordx4 v156, v[126:129], s[4:5] offset:512
	global_store_dwordx4 v156, v[130:133], s[4:5] offset:768
	s_and_saveexec_b64 s[2:3], vcc
	global_store_dwordx2 v157, v[134:135], s[6:7]
	s_branch .LBB0_321
